# ssm_p3 rewritten: fwd+bwd scans paired in one wave (lane halves), 128-step blocks with bwd block-start states from ssm_p1 checkpoints, parked y reused per block (L2-resident)
# baseline (speedup 1.0000x reference)
; #define WSPTR() kptr(224)
; template <bool BWD, int MODE  >
; __device__ __forceinline__ void ssm_pass(const bf16* proj, int rowbase, int g, const bf16x8* BBp, const bf16x8* CCp, float ar, float ai, float& sr, float& si,
;                                          LAS unsigned* XS, int lane, f32x4* ysc, const float* Dp, bf16* zbuf) {
;     ...
;     for (int t = 0; t < 4; ++t) { bb[t] = BBp[t * 64 + lane]; if (MODE > 0) cc[t] = CCp[t * 64 + lane]; }
;     const int ql = lane & 31, hi = lane >> 5;
;     const bf16* up = proj + (size_t)(rowbase + ql) * DIN + 768 + g * 16 + 8 * hi;
;     bf16x8 ucur = *(const bf16x8*)(up + (size_t)(BWD ? 15 : 0) * 32 * DIN);
; __device__ __forceinline__ void ssm_p1(const Args& a, LAS unsigned char* lds, int layer, int G, int vb) {
;     ...
;     for (int wt = gw; wt < 4096; wt += NGW) {
;         const int b = (wt >> 3) & 7, tl = (wt >> 6) * 8 + (wt & 7), dir = tl & 1, seg = (tl >> 1) & 7, g = (tl >> 4) & 31;
;         const int cb = (layer * 2 + dir) * 32 + g;
;         const f32x2 ab = AB[cb * 64 + lane];
;         float sr = 0.f, si = 0.f;
;         const bf16x8* BBp = (const bf16x8*)(WSPTR() + WS_BB) + (size_t)cb * 4 * 64;
;         const int rowbase = b * SEQ + seg * 512;
;         if (dir) ssm_pass<true, 0>(proj, rowbase, g, BBp, nullptr, ab[0], ab[1], sr, si, XS, lane, nullptr, nullptr, nullptr);
;         else     ssm_pass<false, 0>(proj, rowbase, g, BBp, nullptr, ab[0], ab[1], sr, si, XS, lane, nullptr, nullptr, nullptr);
.LBB0_438:
	s_bfe_u32 s27, s18, 0x50007
	s_lshr_b32 s22, s18, 3
	s_or_b32 s28, s27, s26
	s_and_b32 s22, s22, 8
	s_and_b32 s23, s18, 6
	v_lshl_or_b32 v0, s28, 6, v87
	s_or_b32 s36, s22, s23
	v_lshl_add_u64 v[2:3], v[0:1], 3, s[6:7]
	s_movk_i32 s22, 0xe0
	s_lshl_b32 s52, s27, 5
	s_bfe_u32 s37, s18, 0x30003
	global_load_dwordx2 v[98:99], v[2:3], off
	global_load_dwordx2 v[130:131], v[2:3], off offset:256
	s_ashr_i32 s23, s22, 31
	s_add_u32 s22, s0, s22
	s_addc_u32 s23, s1, s23
	s_load_dwordx2 s[22:23], s[22:23], 0x0
	s_lshl_b32 s28, s28, 12
	v_mov_b32_e32 v93, v1
	v_mov_b32_e32 v95, v1
	s_waitcnt lgkmcnt(0)
	s_add_u32 s22, s22, s28
	s_addc_u32 s23, s23, 0
	v_lshl_add_u64 v[2:3], s[22:23], 0, v[92:93]
	v_lshl_add_u64 v[4:5], v[2:3], 0, s[66:67]
	v_add_co_u32_e32 v2, vcc, s46, v2
	s_lshl_b32 s22, s37, 12
	s_nop 0
	v_addc_co_u32_e32 v3, vcc, 0, v3, vcc
	global_load_dwordx4 v[66:69], v[4:5], off offset:1024
	global_load_dwordx4 v[70:73], v[4:5], off offset:2048
	global_load_dwordx4 v[74:77], v[2:3], off
	global_load_dwordx4 v[78:81], v[4:5], off offset:3072
	s_lshl_b32 s23, s36, 8
	s_or_b32 s22, s23, s22
	v_or_b32_e32 v0, s22, v87
	v_mul_u32_u24_e32 v0, 0x500, v0
	v_lshlrev_b32_e32 v2, 1, v0
	v_mov_b32_e32 v3, v1
	v_lshl_add_u64 v[2:3], s[4:5], 0, v[2:3]
	v_lshl_add_u64 v[2:3], v[2:3], 0, s[52:53]
	v_lshl_add_u64 v[2:3], v[2:3], 0, v[94:95]
	s_mov_b64 s[22:23], 0xd800600
	v_lshl_add_u64 v[102:103], v[2:3], 0, s[22:23]
	s_mov_b64 s[22:23], -1
	s_andn2_b64 vcc, exec, s[76:77]
	v_lshl_add_u64 v[100:101], v[0:1], 1, s[52:53]
	s_waitcnt vmcnt(4)
	v_xor_b32_e32 v96, 0x80000000, v99
	s_cbranch_vccnz .LBB0_444
	v_add_co_u32_e32 v2, vcc, 0x12c000, v102
	s_nop 1
	v_addc_co_u32_e32 v3, vcc, 0, v103, vcc
	global_load_dwordx4 v[114:117], v[2:3], off
	v_lshl_add_u64 v[108:109], v[88:89], 0, v[100:101]
	global_load_dwordx4 v[118:121], v[108:109], off
	v_lshl_add_u64 v[108:109], v[108:109], 0, s[68:69]
	global_load_dwordx4 v[122:125], v[108:109], off
	v_lshl_add_u64 v[108:109], v[108:109], 0, s[68:69]
	v_cmp_lt_u32_e32 vcc, 31, v86
	s_nop 1
	v_mul_f32_e32 v215, v98, v98
	v_fma_f32 v215, -v99, v99, v215
	v_mul_f32_e32 v216, v98, v99
	v_fmac_f32_e32 v216, v99, v98
	v_mul_f32_e32 v217, v215, v215
	v_fma_f32 v217, -v216, v216, v217
	v_mul_f32_e32 v194, v215, v216
	v_fmac_f32_e32 v194, v216, v215
	v_mul_f32_e32 v195, v217, v217
	v_fma_f32 v195, -v194, v194, v195
	v_mul_f32_e32 v196, v217, v194
	v_fmac_f32_e32 v196, v194, v217
	v_mul_f32_e32 v197, v195, v195
	v_fma_f32 v197, -v196, v196, v197
	v_mul_f32_e32 v198, v195, v196
	v_fmac_f32_e32 v198, v196, v195
	v_mul_f32_e32 v199, v197, v195
	v_fma_f32 v199, -v198, v196, v199
	v_mul_f32_e32 v200, v197, v196
	v_fmac_f32_e32 v200, v198, v195
	v_mul_f32_e32 v159, v197, v197
	v_fma_f32 v159, -v198, v198, v159
	v_mul_f32_e32 v160, v197, v198
	v_fmac_f32_e32 v160, v198, v197
	v_mov_b32_e32 v201, 1.0
	v_mov_b32_e32 v202, 0
	v_cndmask_b32_e32 v201, v201, v217, vcc
	v_cndmask_b32_e32 v202, v202, v194, vcc
	v_mul_f32_e32 v203, v201, v98
	v_fma_f32 v203, -v202, v99, v203
	v_mul_f32_e32 v204, v201, v99
	v_fmac_f32_e32 v204, v202, v98
	v_mul_f32_e32 v205, v201, v215
	v_fma_f32 v205, -v202, v216, v205
	v_mul_f32_e32 v206, v201, v216
	v_fmac_f32_e32 v206, v202, v215
	v_mul_f32_e32 v207, v205, v98
	v_fma_f32 v207, -v206, v99, v207
	v_mul_f32_e32 v208, v205, v99
	v_fmac_f32_e32 v208, v206, v98
	v_mov_b32_e32 v178, v201
	v_mov_b32_e32 v226, v202
	v_mov_b32_e32 v179, v203
	v_mov_b32_e32 v227, v204
	v_mov_b32_e32 v180, v205
	v_mov_b32_e32 v228, v206
	v_mov_b32_e32 v181, v207
	v_mov_b32_e32 v229, v208
	v_mul_f32_e32 v182, v201, v195
	v_fma_f32 v182, -v202, v196, v182
	v_mul_f32_e32 v230, v201, v196
	v_fmac_f32_e32 v230, v202, v195
	v_mul_f32_e32 v183, v203, v195
	v_fma_f32 v183, -v204, v196, v183
	v_mul_f32_e32 v231, v203, v196
	v_fmac_f32_e32 v231, v204, v195
	v_mul_f32_e32 v184, v205, v195
	v_fma_f32 v184, -v206, v196, v184
	v_mul_f32_e32 v232, v205, v196
	v_fmac_f32_e32 v232, v206, v195
	v_mul_f32_e32 v185, v207, v195
	v_fma_f32 v185, -v208, v196, v185
	v_mul_f32_e32 v233, v207, v196
	v_fmac_f32_e32 v233, v208, v195
	v_mul_f32_e32 v186, v201, v197
	v_fma_f32 v186, -v202, v198, v186
	v_mul_f32_e32 v234, v201, v198
	v_fmac_f32_e32 v234, v202, v197
	v_mul_f32_e32 v187, v203, v197
	v_fma_f32 v187, -v204, v198, v187
	v_mul_f32_e32 v235, v203, v198
	v_fmac_f32_e32 v235, v204, v197
	v_mul_f32_e32 v188, v205, v197
	v_fma_f32 v188, -v206, v198, v188
	v_mul_f32_e32 v236, v205, v198
	v_fmac_f32_e32 v236, v206, v197
	v_mul_f32_e32 v189, v207, v197
	v_fma_f32 v189, -v208, v198, v189
	v_mul_f32_e32 v237, v207, v198
	v_fmac_f32_e32 v237, v208, v197
	v_mul_f32_e32 v190, v201, v199
	v_fma_f32 v190, -v202, v200, v190
	v_mul_f32_e32 v238, v201, v200
	v_fmac_f32_e32 v238, v202, v199
	v_mul_f32_e32 v191, v203, v199
	v_fma_f32 v191, -v204, v200, v191
	v_mul_f32_e32 v239, v203, v200
	v_fmac_f32_e32 v239, v204, v199
	v_mul_f32_e32 v192, v205, v199
	v_fma_f32 v192, -v206, v200, v192
	v_mul_f32_e32 v240, v205, v200
	v_fmac_f32_e32 v240, v206, v199
	v_mul_f32_e32 v193, v207, v199
	v_fma_f32 v193, -v208, v200, v193
	v_mul_f32_e32 v241, v207, v200
	v_fmac_f32_e32 v241, v208, v199
	v_mul_f32_e32 v215, v130, v130
	v_fma_f32 v215, -v131, v131, v215
	v_mul_f32_e32 v216, v130, v131
	v_fmac_f32_e32 v216, v131, v130
	v_mul_f32_e32 v217, v215, v215
	v_fma_f32 v217, -v216, v216, v217
	v_mul_f32_e32 v194, v215, v216
	v_fmac_f32_e32 v194, v216, v215
	v_mul_f32_e32 v195, v217, v217
	v_fma_f32 v195, -v194, v194, v195
	v_mul_f32_e32 v196, v217, v194
	v_fmac_f32_e32 v196, v194, v217
	v_mul_f32_e32 v197, v195, v195
	v_fma_f32 v197, -v196, v196, v197
	v_mul_f32_e32 v198, v195, v196
; #define WSPTR() kptr(224)
; template <bool BWD, int MODE  >
; __device__ __forceinline__ void ssm_pass(const bf16* proj, int rowbase, int g, const bf16x8* BBp, const bf16x8* CCp, float ar, float ai, float& sr, float& si,
;                                          LAS unsigned* XS, int lane, f32x4* ysc, const float* Dp, bf16* zbuf) {
;     ...
;     for (int t = 0; t < 4; ++t) { bb[t] = BBp[t * 64 + lane]; if (MODE > 0) cc[t] = CCp[t * 64 + lane]; }
;     const int ql = lane & 31, hi = lane >> 5;
;     const bf16* up = proj + (size_t)(rowbase + ql) * DIN + 768 + g * 16 + 8 * hi;
;     bf16x8 ucur = *(const bf16x8*)(up + (size_t)(BWD ? 15 : 0) * 32 * DIN);
; __device__ __forceinline__ void ssm_p1(const Args& a, LAS unsigned char* lds, int layer, int G, int vb) {
;     ...
;     for (int wt = gw; wt < 4096; wt += NGW) {
;         const int b = (wt >> 3) & 7, tl = (wt >> 6) * 8 + (wt & 7), dir = tl & 1, seg = (tl >> 1) & 7, g = (tl >> 4) & 31;
;         const int cb = (layer * 2 + dir) * 32 + g;
;         const f32x2 ab = AB[cb * 64 + lane];
;         float sr = 0.f, si = 0.f;
;         const bf16x8* BBp = (const bf16x8*)(WSPTR() + WS_BB) + (size_t)cb * 4 * 64;
;         const int rowbase = b * SEQ + seg * 512;
;         if (dir) ssm_pass<true, 0>(proj, rowbase, g, BBp, nullptr, ab[0], ab[1], sr, si, XS, lane, nullptr, nullptr, nullptr);
;         else     ssm_pass<false, 0>(proj, rowbase, g, BBp, nullptr, ab[0], ab[1], sr, si, XS, lane, nullptr, nullptr, nullptr);
	v_fmac_f32_e32 v198, v196, v195
	v_mul_f32_e32 v199, v197, v195
	v_fma_f32 v199, -v198, v196, v199
	v_mul_f32_e32 v200, v197, v196
	v_fmac_f32_e32 v200, v198, v195
	v_mul_f32_e32 v161, v197, v197
	v_fma_f32 v161, -v198, v198, v161
	v_mul_f32_e32 v214, v197, v198
	v_fmac_f32_e32 v214, v198, v197
	v_mov_b32_e32 v201, 1.0
	v_mov_b32_e32 v202, 0
	v_cndmask_b32_e32 v201, v201, v217, vcc
	v_cndmask_b32_e32 v202, v202, v194, vcc
	v_mul_f32_e32 v203, v201, v130
	v_fma_f32 v203, -v202, v131, v203
	v_mul_f32_e32 v204, v201, v131
	v_fmac_f32_e32 v204, v202, v130
	v_mul_f32_e32 v205, v201, v215
	v_fma_f32 v205, -v202, v216, v205
	v_mul_f32_e32 v206, v201, v216
	v_fmac_f32_e32 v206, v202, v215
	v_mul_f32_e32 v207, v205, v130
	v_fma_f32 v207, -v206, v131, v207
	v_mul_f32_e32 v208, v205, v131
	v_fmac_f32_e32 v208, v206, v130
	v_mov_b32_e32 v134, v201
	v_mov_b32_e32 v242, v202
	v_mov_b32_e32 v135, v203
	v_mov_b32_e32 v243, v204
	v_mov_b32_e32 v136, v205
	v_mov_b32_e32 v244, v206
	v_mov_b32_e32 v137, v207
	v_mov_b32_e32 v245, v208
	v_mul_f32_e32 v138, v201, v195
	v_fma_f32 v138, -v202, v196, v138
	v_mul_f32_e32 v246, v201, v196
	v_fmac_f32_e32 v246, v202, v195
	v_mul_f32_e32 v139, v203, v195
	v_fma_f32 v139, -v204, v196, v139
	v_mul_f32_e32 v247, v203, v196
	v_fmac_f32_e32 v247, v204, v195
	v_mul_f32_e32 v140, v205, v195
	v_fma_f32 v140, -v206, v196, v140
	v_mul_f32_e32 v248, v205, v196
	v_fmac_f32_e32 v248, v206, v195
	v_mul_f32_e32 v141, v207, v195
	v_fma_f32 v141, -v208, v196, v141
	v_mul_f32_e32 v249, v207, v196
	v_fmac_f32_e32 v249, v208, v195
	v_mul_f32_e32 v142, v201, v197
	v_fma_f32 v142, -v202, v198, v142
	v_mul_f32_e32 v250, v201, v198
	v_fmac_f32_e32 v250, v202, v197
	v_mul_f32_e32 v143, v203, v197
	v_fma_f32 v143, -v204, v198, v143
	v_mul_f32_e32 v251, v203, v198
	v_fmac_f32_e32 v251, v204, v197
	v_mul_f32_e32 v144, v205, v197
	v_fma_f32 v144, -v206, v198, v144
	v_mul_f32_e32 v252, v205, v198
	v_fmac_f32_e32 v252, v206, v197
	v_mul_f32_e32 v145, v207, v197
	v_fma_f32 v145, -v208, v198, v145
	v_mul_f32_e32 v253, v207, v198
	v_fmac_f32_e32 v253, v208, v197
	v_mul_f32_e32 v146, v201, v199
	v_fma_f32 v146, -v202, v200, v146
	v_mul_f32_e32 v210, v201, v200
	v_fmac_f32_e32 v210, v202, v199
	v_mul_f32_e32 v147, v203, v199
	v_fma_f32 v147, -v204, v200, v147
	v_mul_f32_e32 v211, v203, v200
	v_fmac_f32_e32 v211, v204, v199
	v_mul_f32_e32 v148, v205, v199
	v_fma_f32 v148, -v206, v200, v148
	v_mul_f32_e32 v212, v205, v200
	v_fmac_f32_e32 v212, v206, v199
	v_mul_f32_e32 v149, v207, v199
	v_fma_f32 v149, -v208, v200, v149
	v_mul_f32_e32 v213, v207, v200
	v_fmac_f32_e32 v213, v208, v199
	v_mov_b32_e32 v150, 0
	v_mov_b32_e32 v151, 0
	v_mov_b32_e32 v152, 0
	v_mov_b32_e32 v153, 0
	s_lshl_b32 s100, s27, 3
	s_lshr_b32 s101, s36, 1
	s_add_i32 s100, s100, s101
	s_lshl_b32 s100, s100, 11
	s_lshl_b32 s101, s37, 23
	s_add_i32 s100, s100, s101
	s_add_u32 s100, s8, s100
	s_addc_u32 s101, s9, 0
	s_sub_u32 s100, s100, 0xa800000
	s_subb_u32 s101, s101, 0
	s_mov_b32 s22, 4
.Lp1b_loop:
	global_load_dwordx4 v[126:129], v[108:109], off
	v_lshl_add_u64 v[108:109], v[108:109], 0, s[68:69]
	s_waitcnt vmcnt(3)
	v_mfma_f32_32x32x16_bf16 v[2:17], v[114:117], v[74:77], 0
	v_mfma_f32_32x32x16_bf16 v[34:49], v[114:117], v[70:73], 0
	v_mfma_f32_32x32x16_bf16 v[18:33], v[114:117], v[66:69], 0
	v_mfma_f32_32x32x16_bf16 v[50:65], v[114:117], v[78:81], 0
	v_mul_f32_e32 v215, v160, v151
	v_mul_f32_e32 v216, v160, v150
	v_fma_f32 v150, v159, v150, -v215
	v_fma_f32 v151, v159, v151, v216
	v_mul_f32_e32 v215, v214, v153
	v_mul_f32_e32 v216, v214, v152
	v_fma_f32 v152, v161, v152, -v215
	v_fma_f32 v153, v161, v153, v216
	s_nop 3
	v_fmac_f32_e32 v150, v178, v2
	v_fmac_f32_e32 v151, v178, v34
	v_fma_f32 v150, -v226, v34, v150
	v_fmac_f32_e32 v151, v226, v2
	v_mul_f32_e32 v217, v179, v3
	v_mul_f32_e32 v194, v179, v35
	v_fma_f32 v217, -v227, v35, v217
	v_fmac_f32_e32 v194, v227, v3
	v_fmac_f32_e32 v150, v180, v4
	v_fmac_f32_e32 v151, v180, v36
	v_fma_f32 v150, -v228, v36, v150
	v_fmac_f32_e32 v151, v228, v4
	v_fmac_f32_e32 v217, v181, v5
	v_fmac_f32_e32 v194, v181, v37
	v_fma_f32 v217, -v229, v37, v217
	v_fmac_f32_e32 v194, v229, v5
	v_fmac_f32_e32 v150, v182, v6
	v_fmac_f32_e32 v151, v182, v38
	v_fma_f32 v150, -v230, v38, v150
	v_fmac_f32_e32 v151, v230, v6
	v_fmac_f32_e32 v217, v183, v7
	v_fmac_f32_e32 v194, v183, v39
	v_fma_f32 v217, -v231, v39, v217
	v_fmac_f32_e32 v194, v231, v7
	v_fmac_f32_e32 v150, v184, v8
	v_fmac_f32_e32 v151, v184, v40
	v_fma_f32 v150, -v232, v40, v150
	v_fmac_f32_e32 v151, v232, v8
	v_fmac_f32_e32 v217, v185, v9
	v_fmac_f32_e32 v194, v185, v41
	v_fma_f32 v217, -v233, v41, v217
	v_fmac_f32_e32 v194, v233, v9
	v_fmac_f32_e32 v150, v186, v10
	v_fmac_f32_e32 v151, v186, v42
	v_fma_f32 v150, -v234, v42, v150
	v_fmac_f32_e32 v151, v234, v10
	v_fmac_f32_e32 v217, v187, v11
	v_fmac_f32_e32 v194, v187, v43
	v_fma_f32 v217, -v235, v43, v217
	v_fmac_f32_e32 v194, v235, v11
	v_fmac_f32_e32 v150, v188, v12
	v_fmac_f32_e32 v151, v188, v44
	v_fma_f32 v150, -v236, v44, v150
	v_fmac_f32_e32 v151, v236, v12
	v_fmac_f32_e32 v217, v189, v13
	v_fmac_f32_e32 v194, v189, v45
	v_fma_f32 v217, -v237, v45, v217
	v_fmac_f32_e32 v194, v237, v13
	v_fmac_f32_e32 v150, v190, v14
	v_fmac_f32_e32 v151, v190, v46
	v_fma_f32 v150, -v238, v46, v150
	v_fmac_f32_e32 v151, v238, v14
	v_fmac_f32_e32 v217, v191, v15
	v_fmac_f32_e32 v194, v191, v47
	v_fma_f32 v217, -v239, v47, v217
	v_fmac_f32_e32 v194, v239, v15
	v_fmac_f32_e32 v150, v192, v16
	v_fmac_f32_e32 v151, v192, v48
	v_fma_f32 v150, -v240, v48, v150
	v_fmac_f32_e32 v151, v240, v16
	v_fmac_f32_e32 v217, v193, v17
	v_fmac_f32_e32 v194, v193, v49
; __device__ __forceinline__ unsigned pk2(float lo, float hi) { const f32x2 v = {lo, hi}; return __builtin_bit_cast(unsigned, __builtin_convertvector(v, bf16x2_t)); }
; __device__ __forceinline__ float bflo(unsigned w) { return __uint_as_float(w << 16); }
; __device__ __forceinline__ float bfhi(unsigned w) { return __uint_as_float(w & 0xffff0000u); }
; #define LDS_FENCE() asm volatile("s_waitcnt lgkmcnt(0)" ::: "memory")
; __device__ __forceinline__ int crow(int r, int hi) { return (r & 3) + 8 * (r >> 2) + 4 * hi; }
; template <bool BWD, int MODE  >
; __device__ __forceinline__ void ssm_pass(const bf16* proj, int rowbase, int g, const bf16x8* BBp, const bf16x8* CCp, float ar, float ai, float& sr, float& si,
;                                          LAS unsigned* XS, int lane, f32x4* ysc, const float* Dp, bf16* zbuf) {
;     ...
;         const f32x16 x0 = __builtin_amdgcn_mfma_f32_32x32x16_bf16(ucur, bb[0], z16, 0, 0, 0);
;         const f32x16 x1 = __builtin_amdgcn_mfma_f32_32x32x16_bf16(ucur, bb[1], z16, 0, 0, 0);
;         const f32x16 x2 = __builtin_amdgcn_mfma_f32_32x32x16_bf16(ucur, bb[2], z16, 0, 0, 0);
;         const f32x16 x3 = __builtin_amdgcn_mfma_f32_32x32x16_bf16(ucur, bb[3], z16, 0, 0, 0);
; #pragma unroll
;         for (int r = 0; r < 16; ++r) { const int t = crow(r, hi); XS[t * XS_STRIDE + ql] = pk2(x0[r], x2[r]); XS[t * XS_STRIDE + 32 + ql] = pk2(x1[r], x3[r]); }
;         LDS_FENCE();
; #pragma unroll
;         for (int tt = 0; tt < 32; ++tt) {
;             const int t = BWD ? 31 - tt : tt;
;             const unsigned v = XS[t * XS_STRIDE + lane];
;             const float nr = fmaf(ar, sr, fmaf(-ai, si, bflo(v))), ni = fmaf(ar, si, fmaf(ai, sr, bfhi(v)));
;             sr = nr; si = ni;
;             if (MODE > 0) XS[t * XS_STRIDE + lane] = pk2(sr, si);
	v_fma_f32 v217, -v241, v49, v217
	v_fmac_f32_e32 v194, v241, v17
	v_add_f32_e32 v150, v150, v217
	v_add_f32_e32 v151, v151, v194
	v_fmac_f32_e32 v152, v134, v18
	v_fmac_f32_e32 v153, v134, v50
	v_fma_f32 v152, -v242, v50, v152
	v_fmac_f32_e32 v153, v242, v18
	v_mul_f32_e32 v195, v135, v19
	v_mul_f32_e32 v196, v135, v51
	v_fma_f32 v195, -v243, v51, v195
	v_fmac_f32_e32 v196, v243, v19
	v_fmac_f32_e32 v152, v136, v20
	v_fmac_f32_e32 v153, v136, v52
	v_fma_f32 v152, -v244, v52, v152
	v_fmac_f32_e32 v153, v244, v20
	v_fmac_f32_e32 v195, v137, v21
	v_fmac_f32_e32 v196, v137, v53
	v_fma_f32 v195, -v245, v53, v195
	v_fmac_f32_e32 v196, v245, v21
	v_fmac_f32_e32 v152, v138, v22
	v_fmac_f32_e32 v153, v138, v54
	v_fma_f32 v152, -v246, v54, v152
	v_fmac_f32_e32 v153, v246, v22
	v_fmac_f32_e32 v195, v139, v23
	v_fmac_f32_e32 v196, v139, v55
	v_fma_f32 v195, -v247, v55, v195
	v_fmac_f32_e32 v196, v247, v23
	v_fmac_f32_e32 v152, v140, v24
	v_fmac_f32_e32 v153, v140, v56
	v_fma_f32 v152, -v248, v56, v152
	v_fmac_f32_e32 v153, v248, v24
	v_fmac_f32_e32 v195, v141, v25
	v_fmac_f32_e32 v196, v141, v57
	v_fma_f32 v195, -v249, v57, v195
	v_fmac_f32_e32 v196, v249, v25
	v_fmac_f32_e32 v152, v142, v26
	v_fmac_f32_e32 v153, v142, v58
	v_fma_f32 v152, -v250, v58, v152
	v_fmac_f32_e32 v153, v250, v26
	v_fmac_f32_e32 v195, v143, v27
	v_fmac_f32_e32 v196, v143, v59
	v_fma_f32 v195, -v251, v59, v195
	v_fmac_f32_e32 v196, v251, v27
	v_fmac_f32_e32 v152, v144, v28
	v_fmac_f32_e32 v153, v144, v60
	v_fma_f32 v152, -v252, v60, v152
	v_fmac_f32_e32 v153, v252, v28
	v_fmac_f32_e32 v195, v145, v29
	v_fmac_f32_e32 v196, v145, v61
	v_fma_f32 v195, -v253, v61, v195
	v_fmac_f32_e32 v196, v253, v29
	v_fmac_f32_e32 v152, v146, v30
	v_fmac_f32_e32 v153, v146, v62
	v_fma_f32 v152, -v210, v62, v152
	v_fmac_f32_e32 v153, v210, v30
	v_fmac_f32_e32 v195, v147, v31
	v_fmac_f32_e32 v196, v147, v63
	v_fma_f32 v195, -v211, v63, v195
	v_fmac_f32_e32 v196, v211, v31
	v_fmac_f32_e32 v152, v148, v32
	v_fmac_f32_e32 v153, v148, v64
	v_fma_f32 v152, -v212, v64, v152
	v_fmac_f32_e32 v153, v212, v32
	v_fmac_f32_e32 v195, v149, v33
	v_fmac_f32_e32 v196, v149, v65
	v_fma_f32 v195, -v213, v65, v195
	v_fmac_f32_e32 v196, v213, v33
	v_add_f32_e32 v152, v152, v195
	v_add_f32_e32 v153, v153, v196
	global_load_dwordx4 v[114:117], v[108:109], off
	v_lshl_add_u64 v[108:109], v[108:109], 0, s[68:69]
	s_waitcnt vmcnt(3)
	v_mfma_f32_32x32x16_bf16 v[2:17], v[118:121], v[74:77], 0
	v_mfma_f32_32x32x16_bf16 v[34:49], v[118:121], v[70:73], 0
	v_mfma_f32_32x32x16_bf16 v[18:33], v[118:121], v[66:69], 0
	v_mfma_f32_32x32x16_bf16 v[50:65], v[118:121], v[78:81], 0
	v_mul_f32_e32 v215, v160, v151
	v_mul_f32_e32 v216, v160, v150
	v_fma_f32 v150, v159, v150, -v215
	v_fma_f32 v151, v159, v151, v216
	v_mul_f32_e32 v215, v214, v153
	v_mul_f32_e32 v216, v214, v152
	v_fma_f32 v152, v161, v152, -v215
	v_fma_f32 v153, v161, v153, v216
	s_nop 3
	v_fmac_f32_e32 v150, v178, v2
	v_fmac_f32_e32 v151, v178, v34
	v_fma_f32 v150, -v226, v34, v150
	v_fmac_f32_e32 v151, v226, v2
	v_mul_f32_e32 v217, v179, v3
	v_mul_f32_e32 v194, v179, v35
	v_fma_f32 v217, -v227, v35, v217
	v_fmac_f32_e32 v194, v227, v3
	v_fmac_f32_e32 v150, v180, v4
	v_fmac_f32_e32 v151, v180, v36
	v_fma_f32 v150, -v228, v36, v150
	v_fmac_f32_e32 v151, v228, v4
	v_fmac_f32_e32 v217, v181, v5
	v_fmac_f32_e32 v194, v181, v37
	v_fma_f32 v217, -v229, v37, v217
	v_fmac_f32_e32 v194, v229, v5
	v_fmac_f32_e32 v150, v182, v6
	v_fmac_f32_e32 v151, v182, v38
	v_fma_f32 v150, -v230, v38, v150
	v_fmac_f32_e32 v151, v230, v6
	v_fmac_f32_e32 v217, v183, v7
	v_fmac_f32_e32 v194, v183, v39
	v_fma_f32 v217, -v231, v39, v217
	v_fmac_f32_e32 v194, v231, v7
	v_fmac_f32_e32 v150, v184, v8
	v_fmac_f32_e32 v151, v184, v40
	v_fma_f32 v150, -v232, v40, v150
	v_fmac_f32_e32 v151, v232, v8
	v_fmac_f32_e32 v217, v185, v9
	v_fmac_f32_e32 v194, v185, v41
	v_fma_f32 v217, -v233, v41, v217
	v_fmac_f32_e32 v194, v233, v9
	v_fmac_f32_e32 v150, v186, v10
	v_fmac_f32_e32 v151, v186, v42
	v_fma_f32 v150, -v234, v42, v150
	v_fmac_f32_e32 v151, v234, v10
	v_fmac_f32_e32 v217, v187, v11
	v_fmac_f32_e32 v194, v187, v43
	v_fma_f32 v217, -v235, v43, v217
	v_fmac_f32_e32 v194, v235, v11
	v_fmac_f32_e32 v150, v188, v12
	v_fmac_f32_e32 v151, v188, v44
	v_fma_f32 v150, -v236, v44, v150
	v_fmac_f32_e32 v151, v236, v12
	v_fmac_f32_e32 v217, v189, v13
	v_fmac_f32_e32 v194, v189, v45
	v_fma_f32 v217, -v237, v45, v217
	v_fmac_f32_e32 v194, v237, v13
	v_fmac_f32_e32 v150, v190, v14
	v_fmac_f32_e32 v151, v190, v46
	v_fma_f32 v150, -v238, v46, v150
	v_fmac_f32_e32 v151, v238, v14
	v_fmac_f32_e32 v217, v191, v15
	v_fmac_f32_e32 v194, v191, v47
	v_fma_f32 v217, -v239, v47, v217
	v_fmac_f32_e32 v194, v239, v15
	v_fmac_f32_e32 v150, v192, v16
	v_fmac_f32_e32 v151, v192, v48
	v_fma_f32 v150, -v240, v48, v150
	v_fmac_f32_e32 v151, v240, v16
	v_fmac_f32_e32 v217, v193, v17
	v_fmac_f32_e32 v194, v193, v49
	v_fma_f32 v217, -v241, v49, v217
	v_fmac_f32_e32 v194, v241, v17
	v_add_f32_e32 v150, v150, v217
	v_add_f32_e32 v151, v151, v194
	v_fmac_f32_e32 v152, v134, v18
	v_fmac_f32_e32 v153, v134, v50
	v_fma_f32 v152, -v242, v50, v152
	v_fmac_f32_e32 v153, v242, v18
	v_mul_f32_e32 v195, v135, v19
	v_mul_f32_e32 v196, v135, v51
	v_fma_f32 v195, -v243, v51, v195
	v_fmac_f32_e32 v196, v243, v19
	v_fmac_f32_e32 v152, v136, v20
	v_fmac_f32_e32 v153, v136, v52
	v_fma_f32 v152, -v244, v52, v152
	v_fmac_f32_e32 v153, v244, v20
	v_fmac_f32_e32 v195, v137, v21
	v_fmac_f32_e32 v196, v137, v53
	v_fma_f32 v195, -v245, v53, v195
	v_fmac_f32_e32 v196, v245, v21
	v_fmac_f32_e32 v152, v138, v22
	v_fmac_f32_e32 v153, v138, v54
	v_fma_f32 v152, -v246, v54, v152
; __device__ __forceinline__ unsigned pk2(float lo, float hi) { const f32x2 v = {lo, hi}; return __builtin_bit_cast(unsigned, __builtin_convertvector(v, bf16x2_t)); }
; __device__ __forceinline__ float bflo(unsigned w) { return __uint_as_float(w << 16); }
; __device__ __forceinline__ float bfhi(unsigned w) { return __uint_as_float(w & 0xffff0000u); }
; #define LDS_FENCE() asm volatile("s_waitcnt lgkmcnt(0)" ::: "memory")
; __device__ __forceinline__ int crow(int r, int hi) { return (r & 3) + 8 * (r >> 2) + 4 * hi; }
; template <bool BWD, int MODE  >
; __device__ __forceinline__ void ssm_pass(const bf16* proj, int rowbase, int g, const bf16x8* BBp, const bf16x8* CCp, float ar, float ai, float& sr, float& si,
;                                          LAS unsigned* XS, int lane, f32x4* ysc, const float* Dp, bf16* zbuf) {
;     ...
;         const f32x16 x0 = __builtin_amdgcn_mfma_f32_32x32x16_bf16(ucur, bb[0], z16, 0, 0, 0);
;         const f32x16 x1 = __builtin_amdgcn_mfma_f32_32x32x16_bf16(ucur, bb[1], z16, 0, 0, 0);
;         const f32x16 x2 = __builtin_amdgcn_mfma_f32_32x32x16_bf16(ucur, bb[2], z16, 0, 0, 0);
;         const f32x16 x3 = __builtin_amdgcn_mfma_f32_32x32x16_bf16(ucur, bb[3], z16, 0, 0, 0);
; #pragma unroll
;         for (int r = 0; r < 16; ++r) { const int t = crow(r, hi); XS[t * XS_STRIDE + ql] = pk2(x0[r], x2[r]); XS[t * XS_STRIDE + 32 + ql] = pk2(x1[r], x3[r]); }
;         LDS_FENCE();
; #pragma unroll
;         for (int tt = 0; tt < 32; ++tt) {
;             const int t = BWD ? 31 - tt : tt;
;             const unsigned v = XS[t * XS_STRIDE + lane];
;             const float nr = fmaf(ar, sr, fmaf(-ai, si, bflo(v))), ni = fmaf(ar, si, fmaf(ai, sr, bfhi(v)));
;             sr = nr; si = ni;
;             if (MODE > 0) XS[t * XS_STRIDE + lane] = pk2(sr, si);
	v_fmac_f32_e32 v153, v246, v22
	v_fmac_f32_e32 v195, v139, v23
	v_fmac_f32_e32 v196, v139, v55
	v_fma_f32 v195, -v247, v55, v195
	v_fmac_f32_e32 v196, v247, v23
	v_fmac_f32_e32 v152, v140, v24
	v_fmac_f32_e32 v153, v140, v56
	v_fma_f32 v152, -v248, v56, v152
	v_fmac_f32_e32 v153, v248, v24
	v_fmac_f32_e32 v195, v141, v25
	v_fmac_f32_e32 v196, v141, v57
	v_fma_f32 v195, -v249, v57, v195
	v_fmac_f32_e32 v196, v249, v25
	v_fmac_f32_e32 v152, v142, v26
	v_fmac_f32_e32 v153, v142, v58
	v_fma_f32 v152, -v250, v58, v152
	v_fmac_f32_e32 v153, v250, v26
	v_fmac_f32_e32 v195, v143, v27
	v_fmac_f32_e32 v196, v143, v59
	v_fma_f32 v195, -v251, v59, v195
	v_fmac_f32_e32 v196, v251, v27
	v_fmac_f32_e32 v152, v144, v28
	v_fmac_f32_e32 v153, v144, v60
	v_fma_f32 v152, -v252, v60, v152
	v_fmac_f32_e32 v153, v252, v28
	v_fmac_f32_e32 v195, v145, v29
	v_fmac_f32_e32 v196, v145, v61
	v_fma_f32 v195, -v253, v61, v195
	v_fmac_f32_e32 v196, v253, v29
	v_fmac_f32_e32 v152, v146, v30
	v_fmac_f32_e32 v153, v146, v62
	v_fma_f32 v152, -v210, v62, v152
	v_fmac_f32_e32 v153, v210, v30
	v_fmac_f32_e32 v195, v147, v31
	v_fmac_f32_e32 v196, v147, v63
	v_fma_f32 v195, -v211, v63, v195
	v_fmac_f32_e32 v196, v211, v31
	v_fmac_f32_e32 v152, v148, v32
	v_fmac_f32_e32 v153, v148, v64
	v_fma_f32 v152, -v212, v64, v152
	v_fmac_f32_e32 v153, v212, v32
	v_fmac_f32_e32 v195, v149, v33
	v_fmac_f32_e32 v196, v149, v65
	v_fma_f32 v195, -v213, v65, v195
	v_fmac_f32_e32 v196, v213, v33
	v_add_f32_e32 v152, v152, v195
	v_add_f32_e32 v153, v153, v196
	global_load_dwordx4 v[118:121], v[108:109], off
	v_lshl_add_u64 v[108:109], v[108:109], 0, s[68:69]
	s_waitcnt vmcnt(3)
	v_mfma_f32_32x32x16_bf16 v[2:17], v[122:125], v[74:77], 0
	v_mfma_f32_32x32x16_bf16 v[34:49], v[122:125], v[70:73], 0
	v_mfma_f32_32x32x16_bf16 v[18:33], v[122:125], v[66:69], 0
	v_mfma_f32_32x32x16_bf16 v[50:65], v[122:125], v[78:81], 0
	v_mul_f32_e32 v215, v160, v151
	v_mul_f32_e32 v216, v160, v150
	v_fma_f32 v150, v159, v150, -v215
	v_fma_f32 v151, v159, v151, v216
	v_mul_f32_e32 v215, v214, v153
	v_mul_f32_e32 v216, v214, v152
	v_fma_f32 v152, v161, v152, -v215
	v_fma_f32 v153, v161, v153, v216
	s_nop 3
	v_fmac_f32_e32 v150, v178, v2
	v_fmac_f32_e32 v151, v178, v34
	v_fma_f32 v150, -v226, v34, v150
	v_fmac_f32_e32 v151, v226, v2
	v_mul_f32_e32 v217, v179, v3
	v_mul_f32_e32 v194, v179, v35
	v_fma_f32 v217, -v227, v35, v217
	v_fmac_f32_e32 v194, v227, v3
	v_fmac_f32_e32 v150, v180, v4
	v_fmac_f32_e32 v151, v180, v36
	v_fma_f32 v150, -v228, v36, v150
	v_fmac_f32_e32 v151, v228, v4
	v_fmac_f32_e32 v217, v181, v5
	v_fmac_f32_e32 v194, v181, v37
	v_fma_f32 v217, -v229, v37, v217
	v_fmac_f32_e32 v194, v229, v5
	v_fmac_f32_e32 v150, v182, v6
	v_fmac_f32_e32 v151, v182, v38
	v_fma_f32 v150, -v230, v38, v150
	v_fmac_f32_e32 v151, v230, v6
	v_fmac_f32_e32 v217, v183, v7
	v_fmac_f32_e32 v194, v183, v39
	v_fma_f32 v217, -v231, v39, v217
	v_fmac_f32_e32 v194, v231, v7
	v_fmac_f32_e32 v150, v184, v8
	v_fmac_f32_e32 v151, v184, v40
	v_fma_f32 v150, -v232, v40, v150
	v_fmac_f32_e32 v151, v232, v8
	v_fmac_f32_e32 v217, v185, v9
	v_fmac_f32_e32 v194, v185, v41
	v_fma_f32 v217, -v233, v41, v217
	v_fmac_f32_e32 v194, v233, v9
	v_fmac_f32_e32 v150, v186, v10
	v_fmac_f32_e32 v151, v186, v42
	v_fma_f32 v150, -v234, v42, v150
	v_fmac_f32_e32 v151, v234, v10
	v_fmac_f32_e32 v217, v187, v11
	v_fmac_f32_e32 v194, v187, v43
	v_fma_f32 v217, -v235, v43, v217
	v_fmac_f32_e32 v194, v235, v11
	v_fmac_f32_e32 v150, v188, v12
	v_fmac_f32_e32 v151, v188, v44
	v_fma_f32 v150, -v236, v44, v150
	v_fmac_f32_e32 v151, v236, v12
	v_fmac_f32_e32 v217, v189, v13
	v_fmac_f32_e32 v194, v189, v45
	v_fma_f32 v217, -v237, v45, v217
	v_fmac_f32_e32 v194, v237, v13
	v_fmac_f32_e32 v150, v190, v14
	v_fmac_f32_e32 v151, v190, v46
	v_fma_f32 v150, -v238, v46, v150
	v_fmac_f32_e32 v151, v238, v14
	v_fmac_f32_e32 v217, v191, v15
	v_fmac_f32_e32 v194, v191, v47
	v_fma_f32 v217, -v239, v47, v217
	v_fmac_f32_e32 v194, v239, v15
	v_fmac_f32_e32 v150, v192, v16
	v_fmac_f32_e32 v151, v192, v48
	v_fma_f32 v150, -v240, v48, v150
	v_fmac_f32_e32 v151, v240, v16
	v_fmac_f32_e32 v217, v193, v17
	v_fmac_f32_e32 v194, v193, v49
	v_fma_f32 v217, -v241, v49, v217
	v_fmac_f32_e32 v194, v241, v17
	v_add_f32_e32 v150, v150, v217
	v_add_f32_e32 v151, v151, v194
	v_fmac_f32_e32 v152, v134, v18
	v_fmac_f32_e32 v153, v134, v50
	v_fma_f32 v152, -v242, v50, v152
	v_fmac_f32_e32 v153, v242, v18
	v_mul_f32_e32 v195, v135, v19
	v_mul_f32_e32 v196, v135, v51
	v_fma_f32 v195, -v243, v51, v195
	v_fmac_f32_e32 v196, v243, v19
	v_fmac_f32_e32 v152, v136, v20
	v_fmac_f32_e32 v153, v136, v52
	v_fma_f32 v152, -v244, v52, v152
	v_fmac_f32_e32 v153, v244, v20
	v_fmac_f32_e32 v195, v137, v21
	v_fmac_f32_e32 v196, v137, v53
	v_fma_f32 v195, -v245, v53, v195
	v_fmac_f32_e32 v196, v245, v21
	v_fmac_f32_e32 v152, v138, v22
	v_fmac_f32_e32 v153, v138, v54
	v_fma_f32 v152, -v246, v54, v152
	v_fmac_f32_e32 v153, v246, v22
	v_fmac_f32_e32 v195, v139, v23
	v_fmac_f32_e32 v196, v139, v55
	v_fma_f32 v195, -v247, v55, v195
	v_fmac_f32_e32 v196, v247, v23
	v_fmac_f32_e32 v152, v140, v24
	v_fmac_f32_e32 v153, v140, v56
	v_fma_f32 v152, -v248, v56, v152
	v_fmac_f32_e32 v153, v248, v24
	v_fmac_f32_e32 v195, v141, v25
	v_fmac_f32_e32 v196, v141, v57
	v_fma_f32 v195, -v249, v57, v195
	v_fmac_f32_e32 v196, v249, v25
	v_fmac_f32_e32 v152, v142, v26
	v_fmac_f32_e32 v153, v142, v58
	v_fma_f32 v152, -v250, v58, v152
	v_fmac_f32_e32 v153, v250, v26
	v_fmac_f32_e32 v195, v143, v27
	v_fmac_f32_e32 v196, v143, v59
	v_fma_f32 v195, -v251, v59, v195
	v_fmac_f32_e32 v196, v251, v27
	v_fmac_f32_e32 v152, v144, v28
	v_fmac_f32_e32 v153, v144, v60
	v_fma_f32 v152, -v252, v60, v152
	v_fmac_f32_e32 v153, v252, v28
	v_fmac_f32_e32 v195, v145, v29
	v_fmac_f32_e32 v196, v145, v61
	v_fma_f32 v195, -v253, v61, v195
	v_fmac_f32_e32 v196, v253, v29
	v_fmac_f32_e32 v152, v146, v30
	v_fmac_f32_e32 v153, v146, v62
	v_fma_f32 v152, -v210, v62, v152
	v_fmac_f32_e32 v153, v210, v30
	v_fmac_f32_e32 v195, v147, v31
	v_fmac_f32_e32 v196, v147, v63
	v_fma_f32 v195, -v211, v63, v195
	v_fmac_f32_e32 v196, v211, v31
	v_fmac_f32_e32 v152, v148, v32
	v_fmac_f32_e32 v153, v148, v64
	v_fma_f32 v152, -v212, v64, v152
	v_fmac_f32_e32 v153, v212, v32
	v_fmac_f32_e32 v195, v149, v33
	v_fmac_f32_e32 v196, v149, v65
	v_fma_f32 v195, -v213, v65, v195
	v_fmac_f32_e32 v196, v213, v33
	v_add_f32_e32 v152, v152, v195
	v_add_f32_e32 v153, v153, v196
	global_load_dwordx4 v[122:125], v[108:109], off
	v_lshl_add_u64 v[108:109], v[108:109], 0, s[68:69]
	s_waitcnt vmcnt(3)
; __device__ __forceinline__ unsigned pk2(float lo, float hi) { const f32x2 v = {lo, hi}; return __builtin_bit_cast(unsigned, __builtin_convertvector(v, bf16x2_t)); }
; __device__ __forceinline__ float bflo(unsigned w) { return __uint_as_float(w << 16); }
; __device__ __forceinline__ float bfhi(unsigned w) { return __uint_as_float(w & 0xffff0000u); }
; #define LDS_FENCE() asm volatile("s_waitcnt lgkmcnt(0)" ::: "memory")
; __device__ __forceinline__ int crow(int r, int hi) { return (r & 3) + 8 * (r >> 2) + 4 * hi; }
; template <bool BWD, int MODE  >
; __device__ __forceinline__ void ssm_pass(const bf16* proj, int rowbase, int g, const bf16x8* BBp, const bf16x8* CCp, float ar, float ai, float& sr, float& si,
;                                          LAS unsigned* XS, int lane, f32x4* ysc, const float* Dp, bf16* zbuf) {
;     ...
;         const f32x16 x0 = __builtin_amdgcn_mfma_f32_32x32x16_bf16(ucur, bb[0], z16, 0, 0, 0);
;         const f32x16 x1 = __builtin_amdgcn_mfma_f32_32x32x16_bf16(ucur, bb[1], z16, 0, 0, 0);
;         const f32x16 x2 = __builtin_amdgcn_mfma_f32_32x32x16_bf16(ucur, bb[2], z16, 0, 0, 0);
;         const f32x16 x3 = __builtin_amdgcn_mfma_f32_32x32x16_bf16(ucur, bb[3], z16, 0, 0, 0);
; #pragma unroll
;         for (int r = 0; r < 16; ++r) { const int t = crow(r, hi); XS[t * XS_STRIDE + ql] = pk2(x0[r], x2[r]); XS[t * XS_STRIDE + 32 + ql] = pk2(x1[r], x3[r]); }
;         LDS_FENCE();
; #pragma unroll
;         for (int tt = 0; tt < 32; ++tt) {
;             const int t = BWD ? 31 - tt : tt;
;             const unsigned v = XS[t * XS_STRIDE + lane];
;             const float nr = fmaf(ar, sr, fmaf(-ai, si, bflo(v))), ni = fmaf(ar, si, fmaf(ai, sr, bfhi(v)));
;             sr = nr; si = ni;
;             if (MODE > 0) XS[t * XS_STRIDE + lane] = pk2(sr, si);
; __device__ __forceinline__ void ssm_p1(const Args& a, LAS unsigned char* lds, int layer, int G, int vb) {
;     ...
;         if (dir) ssm_pass<true, 0>(proj, rowbase, g, BBp, nullptr, ab[0], ab[1], sr, si, XS, lane, nullptr, nullptr, nullptr);
;         else     ssm_pass<false, 0>(proj, rowbase, g, BBp, nullptr, ab[0], ab[1], sr, si, XS, lane, nullptr, nullptr, nullptr);
;         SE[((size_t)((b * 32 + g) * 2 + dir) * 8 + seg) * 64 + lane] = (f32x2){sr, si};
	v_mfma_f32_32x32x16_bf16 v[2:17], v[126:129], v[74:77], 0
	v_mfma_f32_32x32x16_bf16 v[34:49], v[126:129], v[70:73], 0
	v_mfma_f32_32x32x16_bf16 v[18:33], v[126:129], v[66:69], 0
	v_mfma_f32_32x32x16_bf16 v[50:65], v[126:129], v[78:81], 0
	v_mul_f32_e32 v215, v160, v151
	v_mul_f32_e32 v216, v160, v150
	v_fma_f32 v150, v159, v150, -v215
	v_fma_f32 v151, v159, v151, v216
	v_mul_f32_e32 v215, v214, v153
	v_mul_f32_e32 v216, v214, v152
	v_fma_f32 v152, v161, v152, -v215
	v_fma_f32 v153, v161, v153, v216
	s_nop 3
	v_fmac_f32_e32 v150, v178, v2
	v_fmac_f32_e32 v151, v178, v34
	v_fma_f32 v150, -v226, v34, v150
	v_fmac_f32_e32 v151, v226, v2
	v_mul_f32_e32 v217, v179, v3
	v_mul_f32_e32 v194, v179, v35
	v_fma_f32 v217, -v227, v35, v217
	v_fmac_f32_e32 v194, v227, v3
	v_fmac_f32_e32 v150, v180, v4
	v_fmac_f32_e32 v151, v180, v36
	v_fma_f32 v150, -v228, v36, v150
	v_fmac_f32_e32 v151, v228, v4
	v_fmac_f32_e32 v217, v181, v5
	v_fmac_f32_e32 v194, v181, v37
	v_fma_f32 v217, -v229, v37, v217
	v_fmac_f32_e32 v194, v229, v5
	v_fmac_f32_e32 v150, v182, v6
	v_fmac_f32_e32 v151, v182, v38
	v_fma_f32 v150, -v230, v38, v150
	v_fmac_f32_e32 v151, v230, v6
	v_fmac_f32_e32 v217, v183, v7
	v_fmac_f32_e32 v194, v183, v39
	v_fma_f32 v217, -v231, v39, v217
	v_fmac_f32_e32 v194, v231, v7
	v_fmac_f32_e32 v150, v184, v8
	v_fmac_f32_e32 v151, v184, v40
	v_fma_f32 v150, -v232, v40, v150
	v_fmac_f32_e32 v151, v232, v8
	v_fmac_f32_e32 v217, v185, v9
	v_fmac_f32_e32 v194, v185, v41
	v_fma_f32 v217, -v233, v41, v217
	v_fmac_f32_e32 v194, v233, v9
	v_fmac_f32_e32 v150, v186, v10
	v_fmac_f32_e32 v151, v186, v42
	v_fma_f32 v150, -v234, v42, v150
	v_fmac_f32_e32 v151, v234, v10
	v_fmac_f32_e32 v217, v187, v11
	v_fmac_f32_e32 v194, v187, v43
	v_fma_f32 v217, -v235, v43, v217
	v_fmac_f32_e32 v194, v235, v11
	v_fmac_f32_e32 v150, v188, v12
	v_fmac_f32_e32 v151, v188, v44
	v_fma_f32 v150, -v236, v44, v150
	v_fmac_f32_e32 v151, v236, v12
	v_fmac_f32_e32 v217, v189, v13
	v_fmac_f32_e32 v194, v189, v45
	v_fma_f32 v217, -v237, v45, v217
	v_fmac_f32_e32 v194, v237, v13
	v_fmac_f32_e32 v150, v190, v14
	v_fmac_f32_e32 v151, v190, v46
	v_fma_f32 v150, -v238, v46, v150
	v_fmac_f32_e32 v151, v238, v14
	v_fmac_f32_e32 v217, v191, v15
	v_fmac_f32_e32 v194, v191, v47
	v_fma_f32 v217, -v239, v47, v217
	v_fmac_f32_e32 v194, v239, v15
	v_fmac_f32_e32 v150, v192, v16
	v_fmac_f32_e32 v151, v192, v48
	v_fma_f32 v150, -v240, v48, v150
	v_fmac_f32_e32 v151, v240, v16
	v_fmac_f32_e32 v217, v193, v17
	v_fmac_f32_e32 v194, v193, v49
	v_fma_f32 v217, -v241, v49, v217
	v_fmac_f32_e32 v194, v241, v17
	v_add_f32_e32 v150, v150, v217
	v_add_f32_e32 v151, v151, v194
	v_fmac_f32_e32 v152, v134, v18
	v_fmac_f32_e32 v153, v134, v50
	v_fma_f32 v152, -v242, v50, v152
	v_fmac_f32_e32 v153, v242, v18
	v_mul_f32_e32 v195, v135, v19
	v_mul_f32_e32 v196, v135, v51
	v_fma_f32 v195, -v243, v51, v195
	v_fmac_f32_e32 v196, v243, v19
	v_fmac_f32_e32 v152, v136, v20
	v_fmac_f32_e32 v153, v136, v52
	v_fma_f32 v152, -v244, v52, v152
	v_fmac_f32_e32 v153, v244, v20
	v_fmac_f32_e32 v195, v137, v21
	v_fmac_f32_e32 v196, v137, v53
	v_fma_f32 v195, -v245, v53, v195
	v_fmac_f32_e32 v196, v245, v21
	v_fmac_f32_e32 v152, v138, v22
	v_fmac_f32_e32 v153, v138, v54
	v_fma_f32 v152, -v246, v54, v152
	v_fmac_f32_e32 v153, v246, v22
	v_fmac_f32_e32 v195, v139, v23
	v_fmac_f32_e32 v196, v139, v55
	v_fma_f32 v195, -v247, v55, v195
	v_fmac_f32_e32 v196, v247, v23
	v_fmac_f32_e32 v152, v140, v24
	v_fmac_f32_e32 v153, v140, v56
	v_fma_f32 v152, -v248, v56, v152
	v_fmac_f32_e32 v153, v248, v24
	v_fmac_f32_e32 v195, v141, v25
	v_fmac_f32_e32 v196, v141, v57
	v_fma_f32 v195, -v249, v57, v195
	v_fmac_f32_e32 v196, v249, v25
	v_fmac_f32_e32 v152, v142, v26
	v_fmac_f32_e32 v153, v142, v58
	v_fma_f32 v152, -v250, v58, v152
	v_fmac_f32_e32 v153, v250, v26
	v_fmac_f32_e32 v195, v143, v27
	v_fmac_f32_e32 v196, v143, v59
	v_fma_f32 v195, -v251, v59, v195
	v_fmac_f32_e32 v196, v251, v27
	v_fmac_f32_e32 v152, v144, v28
	v_fmac_f32_e32 v153, v144, v60
	v_fma_f32 v152, -v252, v60, v152
	v_fmac_f32_e32 v153, v252, v28
	v_fmac_f32_e32 v195, v145, v29
	v_fmac_f32_e32 v196, v145, v61
	v_fma_f32 v195, -v253, v61, v195
	v_fmac_f32_e32 v196, v253, v29
	v_fmac_f32_e32 v152, v146, v30
	v_fmac_f32_e32 v153, v146, v62
	v_fma_f32 v152, -v210, v62, v152
	v_fmac_f32_e32 v153, v210, v30
	v_fmac_f32_e32 v195, v147, v31
	v_fmac_f32_e32 v196, v147, v63
	v_fma_f32 v195, -v211, v63, v195
	v_fmac_f32_e32 v196, v211, v31
	v_fmac_f32_e32 v152, v148, v32
	v_fmac_f32_e32 v153, v148, v64
	v_fma_f32 v152, -v212, v64, v152
	v_fmac_f32_e32 v153, v212, v32
	v_fmac_f32_e32 v195, v149, v33
	v_fmac_f32_e32 v196, v149, v65
	v_fma_f32 v195, -v213, v65, v195
	v_fmac_f32_e32 v196, v213, v33
	v_add_f32_e32 v152, v152, v195
	v_add_f32_e32 v153, v153, v196
	s_cmp_eq_u32 s22, 1
	s_cbranch_scc1 .Lp1b_nochk
	v_mov_b32_e32 v198, v150
	v_mov_b32_e32 v199, v151
	v_mov_b32_e32 v200, v152
	v_mov_b32_e32 v201, v153
	s_nop 1
	v_permlane32_swap_b32_e32 v198, v200
	v_permlane32_swap_b32_e32 v199, v201
	v_add_f32_e32 v198, v198, v200
	v_add_f32_e32 v199, v199, v201
	v_lshlrev_b32_e32 v202, 3, v86
	global_store_dwordx2 v202, v[198:199], s[100:101]
	s_add_u32 s100, s100, 0x200
	s_addc_u32 s101, s101, 0
.Lp1b_nochk:
	s_add_i32 s22, s22, -1
	s_cmp_lg_u32 s22, 0
	s_cbranch_scc1 .Lp1b_loop
	s_nop 1
	v_permlane32_swap_b32_e32 v150, v152
	v_permlane32_swap_b32_e32 v151, v153
	v_add_f32_e32 v111, v150, v152
	v_add_f32_e32 v110, v151, v153

; #define INP(k) inptr(k)
; #define WSPTR() kptr(224)
; __device__ __forceinline__ void ssm_p3(const Args& a, LAS unsigned char* lds, int layer, int G, int vb) {
;     ...
;     for (int wg = vb; wg < 256; wg += G) {
;         const int wt = wg * 8 + wave, b = wg & 7, g = ((wg >> 3) & 3) * 8 + wave, seg = wg >> 5;
;         const int rowbase = b * SEQ + seg * 512;
;         f32x4* ysc = (f32x4*)(WSPTR() + WS_YSCR) + (size_t)wt * (16 * 2 * 64);
;         {
;             const int cb = (layer * 2 + 1) * 32 + g;
;             const f32x2 ab = AB[cb * 64 + lane], ap = AP[cb * 64 + lane];
;             const f32x2* se = SE + ((size_t)((b * 32 + g) * 2 + 1) * 8) * 64 + lane;
;             float sr = 0.f, si = 0.f;
;             for (int k = 7; k > seg && !DIAG_NOCARRY; --k) { const f32x2 e = se[k * 64]; const float nr = ap[0] * sr - ap[1] * si + e[0], ni = ap[0] * si + ap[1] * sr + e[1]; sr = nr; si = ni; }
;             ssm_pass<true, 1>(proj, rowbase, g, (const bf16x8*)(WSPTR() + WS_BB) + (size_t)cb * 256, (const bf16x8*)(WSPTR() + WS_CC) + (size_t)cb * 256, ab[0], ab[1], sr, si, XS, lane, ysc, nullptr, nullptr);
;         }
;         {
;             const int cb = (layer * 2 + 0) * 32 + g;
;             const f32x2 ab = AB[cb * 64 + lane], ap = AP[cb * 64 + lane];
;             const f32x2* se = SE + ((size_t)((b * 32 + g) * 2 + 0) * 8) * 64 + lane;
;             float sr = 0.f, si = 0.f;
;             for (int k = 0; k < seg && !DIAG_NOCARRY; ++k) { const f32x2 e = se[k * 64]; const float nr = ap[0] * sr - ap[1] * si + e[0], ni = ap[0] * si + ap[1] * sr + e[1]; sr = nr; si = ni; }
;             ssm_pass<false, 2>(proj, rowbase, g, (const bf16x8*)(WSPTR() + WS_BB) + (size_t)cb * 256, (const bf16x8*)(WSPTR() + WS_CC) + (size_t)cb * 256, ab[0], ab[1], sr, si, XS, lane, ysc, INP(16) + layer * 512, zbuf);
.LBB0_502:
	s_or_b64 exec, exec, s[4:5]
	v_readlane_b32 s18, v254, 3
	s_waitcnt lgkmcnt(0)
	v_mov_b32_e32 v2, v209
	v_readlane_b32 s19, v254, 4
	s_barrier
	s_lshl_b32 s52, s17, 9
	s_movk_i32 s4, 0xe0
	v_readfirstlane_b32 s5, v2
	s_movk_i32 s6, 0xe0
	s_movk_i32 s8, 0xe0
	s_movk_i32 s26, 0xe0
	s_movk_i32 s23, 0xe0
	s_and_b64 vcc, exec, s[18:19]
	s_cbranch_vccz .LBB0_521
	s_ashr_i32 s18, s5, 6
	s_load_dwordx2 s[4:5], s[0:1], 0xe0
	s_load_dwordx2 s[28:29], s[0:1], 0x80
	v_and_b32_e32 v181, 63, v209
	v_lshlrev_b32_e32 v180, 3, v181
	v_lshlrev_b32_e32 v0, 4, v181
	s_mov_b32 s60, 0x0f0f0f0f
	s_mov_b32 s61, 0x0f0f0f0f
	s_mov_b32 s62, 0xf0f0f0f0
	s_mov_b32 s63, 0xf0f0f0f0
	s_mov_b32 s58, s33
	s_waitcnt lgkmcnt(0)
	s_add_u32 s6, s4, 0xd800000
	s_addc_u32 s7, s5, 0
	s_add_u32 s8, s4, 0x16800000
	s_addc_u32 s9, s5, 0
	s_add_u32 s80, s6, 0x1400
	s_addc_u32 s81, s7, 0
	s_sub_u32 s82, s6, 0x1400
	s_subb_u32 s83, s7, 0
	s_mul_i32 s26, s18, 0x2200
	s_add_i32 s26, s26, 0x4000
	v_and_b32_e32 v179, 31, v181
	v_lshrrev_b32_e32 v225, 5, v181
	v_mul_u32_u24_e32 v225, 0x1100, v225
	v_lshl_add_u32 v179, v179, 2, v225
	v_add_u32_e32 v158, s26, v179
	v_add_u32_e32 v159, 1088, v158
	v_add_u32_e32 v160, 2176, v158
	v_add_u32_e32 v161, 3264, v158
	v_and_b32_e32 v179, 15, v181
	v_mul_u32_u24_e32 v179, 0x110, v179
	v_lshrrev_b32_e32 v225, 4, v181
	v_lshl_add_u32 v179, v225, 4, v179
	v_add_u32_e32 v178, s26, v179
.Lp3n_task:
	v_and_b32_e32 v181, 63, v209
	v_lshlrev_b32_e32 v180, 3, v181
	s_and_b32 s54, s58, 7
	s_bfe_u32 s26, s58, 0x20003
	s_lshr_b32 s55, s58, 5
	s_lshl_b32 s26, s26, 3
	s_add_i32 s59, s26, s18
	s_lshl_b32 s22, s54, 12
	s_lshl_b32 s26, s55, 9
	s_add_i32 s22, s22, s26
	s_lshl_b32 s23, s17, 6
	s_add_i32 s23, s23, s59
	s_lshl_b32 s26, s23, 9
	s_add_u32 s36, s4, s26
	s_addc_u32 s37, s5, 0
	s_add_u32 s36, s36, 0x1d500000
	s_addc_u32 s37, s37, 0
	global_load_dwordx2 v[146:147], v180, s[36:37]
	s_add_u32 s38, s36, 0x4000
	s_addc_u32 s39, s37, 0
	global_load_dwordx2 v[148:149], v180, s[38:39]
	s_add_u32 s38, s36, 0x40000
	s_addc_u32 s39, s37, 0
	global_load_dwordx2 v[204:205], v180, s[38:39]
	s_add_u32 s38, s36, 0x44000
	s_addc_u32 s39, s37, 0
	global_load_dwordx2 v[206:207], v180, s[38:39]
	s_lshl_b32 s26, s54, 5
	s_add_i32 s26, s26, s59
	s_lshl_b32 s26, s26, 13
	s_add_u32 s38, s4, s26
	s_addc_u32 s39, s5, 0
	s_add_u32 s38, s38, 0x1d000000
	s_addc_u32 s39, s39, 0
	global_load_dwordx2 v[2:3], v180, s[38:39] offset:0
	global_load_dwordx2 v[4:5], v180, s[38:39] offset:512
	global_load_dwordx2 v[6:7], v180, s[38:39] offset:1024
	global_load_dwordx2 v[8:9], v180, s[38:39] offset:1536
	global_load_dwordx2 v[10:11], v180, s[38:39] offset:2048
	global_load_dwordx2 v[12:13], v180, s[38:39] offset:2560
	global_load_dwordx2 v[14:15], v180, s[38:39] offset:3072
	s_add_u32 s38, s38, 0x1000
	s_addc_u32 s39, s39, 0
	global_load_dwordx2 v[20:21], v180, s[38:39] offset:512
	global_load_dwordx2 v[22:23], v180, s[38:39] offset:1024
	global_load_dwordx2 v[24:25], v180, s[38:39] offset:1536
	global_load_dwordx2 v[26:27], v180, s[38:39] offset:2048
	global_load_dwordx2 v[28:29], v180, s[38:39] offset:2560
	global_load_dwordx2 v[30:31], v180, s[38:39] offset:3072
	global_load_dwordx2 v[32:33], v180, s[38:39] offset:3584
	s_lshl_b32 s26, s59, 3
	s_add_i32 s26, s26, s55
	s_lshl_b32 s26, s26, 11
	s_lshl_b32 s27, s54, 23
	s_add_i32 s26, s26, s27
	s_add_u32 s38, s4, s26
	s_addc_u32 s39, s5, 0
	s_add_u32 s38, s38, 0x12800000
	s_addc_u32 s39, s39, 0
	global_load_dwordx2 v[44:45], v180, s[38:39] offset:0
	global_load_dwordx2 v[46:47], v180, s[38:39] offset:512
	global_load_dwordx2 v[48:49], v180, s[38:39] offset:1024
	s_lshl_b32 s26, s23, 12
	s_add_u32 s38, s4, s26
	s_addc_u32 s39, s5, 0
	s_add_u32 s38, s38, 0x1d600000
	s_addc_u32 s39, s39, 0
	global_load_dwordx4 v[66:69], v0, s[38:39] offset:0
	global_load_dwordx4 v[70:73], v0, s[38:39] offset:1024
	global_load_dwordx4 v[74:77], v0, s[38:39] offset:2048
	global_load_dwordx4 v[78:81], v0, s[38:39] offset:3072
	s_add_u32 s36, s38, 0x20000
	s_addc_u32 s37, s39, 0
	global_load_dwordx4 v[82:85], v0, s[36:37] offset:0
	global_load_dwordx4 v[86:89], v0, s[36:37] offset:1024
	global_load_dwordx4 v[90:93], v0, s[36:37] offset:2048
	global_load_dwordx4 v[94:97], v0, s[36:37] offset:3072
	s_add_u32 s36, s38, 0x100000
	s_addc_u32 s37, s39, 0
	global_load_dwordx4 v[98:101], v0, s[36:37] offset:0
	global_load_dwordx4 v[102:105], v0, s[36:37] offset:1024
	global_load_dwordx4 v[106:109], v0, s[36:37] offset:2048
	global_load_dwordx4 v[110:113], v0, s[36:37] offset:3072
	s_add_u32 s36, s38, 0x120000
	s_addc_u32 s37, s39, 0
	global_load_dwordx4 v[114:117], v0, s[36:37] offset:0
	global_load_dwordx4 v[118:121], v0, s[36:37] offset:1024
	global_load_dwordx4 v[122:125], v0, s[36:37] offset:2048
	global_load_dwordx4 v[126:129], v0, s[36:37] offset:3072
	s_lshl_b32 s26, s59, 4
	s_add_i32 s26, s26, s52
	s_lshl_b32 s26, s26, 2
	s_add_u32 s36, s28, s26
	s_addc_u32 s37, s29, 0
	v_and_b32_e32 v179, 15, v181
	v_lshlrev_b32_e32 v179, 2, v179
	global_load_dword v208, v179, s[36:37]
	s_lshl_b32 s26, s58, 3
	s_add_i32 s26, s26, s18
	s_lshr_b32 s27, s26, 17
	s_lshl_b32 s26, s26, 15
	s_add_u32 s78, s4, s26
	s_addc_u32 s79, s5, s27
	s_add_u32 s78, s78, 0x19000000
	s_addc_u32 s79, s79, 0
	v_and_b32_e32 v179, 3, v181
	v_bfe_u32 v225, v181, 3, 2
	v_lshl_add_u32 v179, v225, 2, v179
	v_sub_u32_e32 v225, 0x7f, v179
	v_and_b32_e32 v156, 4, v181
	v_cmp_eq_u32_e32 vcc, 0, v156
	s_nop 1
	v_cndmask_b32_e32 v179, v225, v179, vcc
	v_add_u32_e32 v179, s22, v179
	v_mul_u32_u24_e32 v179, 0xa00, v179
	v_lshrrev_b32_e32 v225, 5, v181
	v_lshl_add_u32 v179, v225, 4, v179
	s_lshl_b32 s26, s59, 5
	s_addk_i32 s26, 0x600
	v_add_u32_e32 v156, s26, v179
	v_mov_b32_e32 v179, 0xa000
	v_mov_b32_e32 v225, 0xffff6000
	v_cndmask_b32_e32 v157, v225, v179, vcc
	v_mov_b32_e32 v130, 0
	v_mov_b32_e32 v131, 0
	v_mov_b32_e32 v132, 0
	v_mov_b32_e32 v133, 0
	v_mov_b32_e32 v134, 0
	v_mov_b32_e32 v135, 0
	v_mov_b32_e32 v136, 0
	v_mov_b32_e32 v137, 0
	v_mov_b32_e32 v138, 0
	v_mov_b32_e32 v139, 0
	v_mov_b32_e32 v140, 0
	v_mov_b32_e32 v141, 0
	v_mov_b32_e32 v142, 0
	v_mov_b32_e32 v143, 0
	v_mov_b32_e32 v144, 0
	v_mov_b32_e32 v145, 0
	s_mov_b64 exec, s[60:61]
	global_load_dwordx4 v[130:133], v156, s[6:7]
	s_mov_b64 exec, s[62:63]
	global_load_dwordx4 v[134:137], v156, s[6:7]
	s_mov_b64 exec, -1
	s_waitcnt vmcnt(0)
	v_mov_b32_e32 v152, 0
	v_mov_b32_e32 v153, 0
	v_mov_b32_e32 v154, 0
	v_mov_b32_e32 v155, 0
	s_cmp_le_u32 s55, 0
	s_cbranch_scc1 .Lp3n_fdone
; #define WSPTR() kptr(224)
; __device__ __forceinline__ void ssm_p3(const Args& a, LAS unsigned char* lds, int layer, int G, int vb) {
;     ...
;             const int cb = (layer * 2 + 1) * 32 + g;
;             const f32x2 ab = AB[cb * 64 + lane], ap = AP[cb * 64 + lane];
;             const f32x2* se = SE + ((size_t)((b * 32 + g) * 2 + 1) * 8) * 64 + lane;
;             float sr = 0.f, si = 0.f;
;             for (int k = 7; k > seg && !DIAG_NOCARRY; --k) { const f32x2 e = se[k * 64]; const float nr = ap[0] * sr - ap[1] * si + e[0], ni = ap[0] * si + ap[1] * sr + e[1]; sr = nr; si = ni; }
;             ssm_pass<true, 1>(proj, rowbase, g, (const bf16x8*)(WSPTR() + WS_BB) + (size_t)cb * 256, (const bf16x8*)(WSPTR() + WS_CC) + (size_t)cb * 256, ab[0], ab[1], sr, si, XS, lane, ysc, nullptr, nullptr);
;         }
;         {
;             const int cb = (layer * 2 + 0) * 32 + g;
;             const f32x2 ab = AB[cb * 64 + lane], ap = AP[cb * 64 + lane];
;             const f32x2* se = SE + ((size_t)((b * 32 + g) * 2 + 0) * 8) * 64 + lane;
;             float sr = 0.f, si = 0.f;
;             for (int k = 0; k < seg && !DIAG_NOCARRY; ++k) { const f32x2 e = se[k * 64]; const float nr = ap[0] * sr - ap[1] * si + e[0], ni = ap[0] * si + ap[1] * sr + e[1]; sr = nr; si = ni; }
	v_mul_f32_e32 v179, v205, v153
	v_mul_f32_e32 v225, v204, v153
	v_fma_f32 v179, v204, v152, -v179
	v_fma_f32 v225, v205, v152, v225
	v_add_f32_e32 v152, v179, v2
	v_add_f32_e32 v153, v225, v3
	s_cmp_le_u32 s55, 1
	s_cbranch_scc1 .Lp3n_fdone
	v_mul_f32_e32 v179, v205, v153
	v_mul_f32_e32 v225, v204, v153
	v_fma_f32 v179, v204, v152, -v179
	v_fma_f32 v225, v205, v152, v225
	v_add_f32_e32 v152, v179, v4
	v_add_f32_e32 v153, v225, v5
	s_cmp_le_u32 s55, 2
	s_cbranch_scc1 .Lp3n_fdone
	v_mul_f32_e32 v179, v205, v153
	v_mul_f32_e32 v225, v204, v153
	v_fma_f32 v179, v204, v152, -v179
	v_fma_f32 v225, v205, v152, v225
	v_add_f32_e32 v152, v179, v6
	v_add_f32_e32 v153, v225, v7
	s_cmp_le_u32 s55, 3
	s_cbranch_scc1 .Lp3n_fdone
	v_mul_f32_e32 v179, v205, v153
	v_mul_f32_e32 v225, v204, v153
	v_fma_f32 v179, v204, v152, -v179
	v_fma_f32 v225, v205, v152, v225
	v_add_f32_e32 v152, v179, v8
	v_add_f32_e32 v153, v225, v9
	s_cmp_le_u32 s55, 4
	s_cbranch_scc1 .Lp3n_fdone
	v_mul_f32_e32 v179, v205, v153
	v_mul_f32_e32 v225, v204, v153
	v_fma_f32 v179, v204, v152, -v179
	v_fma_f32 v225, v205, v152, v225
	v_add_f32_e32 v152, v179, v10
	v_add_f32_e32 v153, v225, v11
	s_cmp_le_u32 s55, 5
	s_cbranch_scc1 .Lp3n_fdone
	v_mul_f32_e32 v179, v205, v153
	v_mul_f32_e32 v225, v204, v153
	v_fma_f32 v179, v204, v152, -v179
	v_fma_f32 v225, v205, v152, v225
	v_add_f32_e32 v152, v179, v12
	v_add_f32_e32 v153, v225, v13
	s_cmp_le_u32 s55, 6
	s_cbranch_scc1 .Lp3n_fdone
	v_mul_f32_e32 v179, v205, v153
	v_mul_f32_e32 v225, v204, v153
	v_fma_f32 v179, v204, v152, -v179
	v_fma_f32 v225, v205, v152, v225
	v_add_f32_e32 v152, v179, v14
	v_add_f32_e32 v153, v225, v15
.Lp3n_fdone:
	s_cmp_ge_u32 s55, 7
	s_cbranch_scc1 .Lp3n_bdone
	v_mul_f32_e32 v179, v207, v155
	v_mul_f32_e32 v225, v206, v155
	v_fma_f32 v179, v206, v154, -v179
	v_fma_f32 v225, v207, v154, v225
	v_add_f32_e32 v154, v179, v32
	v_add_f32_e32 v155, v225, v33
	s_cmp_ge_u32 s55, 6
	s_cbranch_scc1 .Lp3n_bdone
	v_mul_f32_e32 v179, v207, v155
	v_mul_f32_e32 v225, v206, v155
	v_fma_f32 v179, v206, v154, -v179
	v_fma_f32 v225, v207, v154, v225
	v_add_f32_e32 v154, v179, v30
	v_add_f32_e32 v155, v225, v31
	s_cmp_ge_u32 s55, 5
	s_cbranch_scc1 .Lp3n_bdone
	v_mul_f32_e32 v179, v207, v155
	v_mul_f32_e32 v225, v206, v155
	v_fma_f32 v179, v206, v154, -v179
	v_fma_f32 v225, v207, v154, v225
	v_add_f32_e32 v154, v179, v28
	v_add_f32_e32 v155, v225, v29
	s_cmp_ge_u32 s55, 4
	s_cbranch_scc1 .Lp3n_bdone
	v_mul_f32_e32 v179, v207, v155
	v_mul_f32_e32 v225, v206, v155
	v_fma_f32 v179, v206, v154, -v179
	v_fma_f32 v225, v207, v154, v225
	v_add_f32_e32 v154, v179, v26
	v_add_f32_e32 v155, v225, v27
	s_cmp_ge_u32 s55, 3
	s_cbranch_scc1 .Lp3n_bdone
	v_mul_f32_e32 v179, v207, v155
	v_mul_f32_e32 v225, v206, v155
	v_fma_f32 v179, v206, v154, -v179
	v_fma_f32 v225, v207, v154, v225
	v_add_f32_e32 v154, v179, v24
	v_add_f32_e32 v155, v225, v25
	s_cmp_ge_u32 s55, 2
	s_cbranch_scc1 .Lp3n_bdone
	v_mul_f32_e32 v179, v207, v155
	v_mul_f32_e32 v225, v206, v155
	v_fma_f32 v179, v206, v154, -v179
	v_fma_f32 v225, v207, v154, v225
	v_add_f32_e32 v154, v179, v22
	v_add_f32_e32 v155, v225, v23
	s_cmp_ge_u32 s55, 1
	s_cbranch_scc1 .Lp3n_bdone
	v_mul_f32_e32 v179, v207, v155
	v_mul_f32_e32 v225, v206, v155
	v_fma_f32 v179, v206, v154, -v179
	v_fma_f32 v225, v207, v154, v225
	v_add_f32_e32 v154, v179, v20
	v_add_f32_e32 v155, v225, v21
.Lp3n_bdone:
	v_mov_b32_e32 v34, v148
	v_mov_b32_e32 v35, v149
	v_mul_f32_e32 v36, v34, v34
	v_fma_f32 v36, -v35, v35, v36
	v_mul_f32_e32 v37, v34, v35
	v_fmac_f32_e32 v37, v35, v34
	v_mov_b32_e32 v34, v36
	v_mov_b32_e32 v35, v37
	v_mul_f32_e32 v36, v34, v34
	v_fma_f32 v36, -v35, v35, v36
	v_mul_f32_e32 v37, v34, v35
	v_fmac_f32_e32 v37, v35, v34
	v_mov_b32_e32 v34, v36
	v_mov_b32_e32 v35, v37
	v_mul_f32_e32 v36, v34, v34
	v_fma_f32 v36, -v35, v35, v36
	v_mul_f32_e32 v37, v34, v35
	v_fmac_f32_e32 v37, v35, v34
	v_mov_b32_e32 v34, v36
	v_mov_b32_e32 v35, v37
	v_mul_f32_e32 v36, v34, v34
	v_fma_f32 v36, -v35, v35, v36
	v_mul_f32_e32 v37, v34, v35
	v_fmac_f32_e32 v37, v35, v34
	v_mov_b32_e32 v34, v36
	v_mov_b32_e32 v35, v37
	v_mul_f32_e32 v36, v34, v34
	v_fma_f32 v36, -v35, v35, v36
	v_mul_f32_e32 v37, v34, v35
	v_fmac_f32_e32 v37, v35, v34
	v_mov_b32_e32 v34, v36
	v_mov_b32_e32 v35, v37
	v_mul_f32_e32 v36, v34, v34
	v_fma_f32 v36, -v35, v35, v36
	v_mul_f32_e32 v37, v34, v35
	v_fmac_f32_e32 v37, v35, v34
	v_mov_b32_e32 v34, v36
	v_mov_b32_e32 v35, v37
	v_mul_f32_e32 v36, v34, v34
	v_fma_f32 v36, -v35, v35, v36
	v_mul_f32_e32 v37, v34, v35
	v_fmac_f32_e32 v37, v35, v34
	v_mov_b32_e32 v34, v36
	v_mov_b32_e32 v35, v37
	s_lshl_b32 s26, s18, 11
	v_lshl_add_u32 v38, v181, 3, s26
	v_mov_b32_e32 v40, v154
	v_mov_b32_e32 v41, v155
	ds_write_b64 v38, v[40:41] offset:1536
	v_mul_f32_e32 v36, v35, v41
	v_mul_f32_e32 v37, v34, v41
	v_fma_f32 v36, v34, v40, -v36
	v_fma_f32 v37, v35, v40, v37
	v_mov_b32_e32 v40, v36
	v_mov_b32_e32 v41, v37
	v_add_f32_e32 v42, v40, v44
	v_add_f32_e32 v43, v41, v45
	ds_write_b64 v38, v[42:43] offset:1024
	v_mul_f32_e32 v36, v35, v41
	v_mul_f32_e32 v37, v34, v41
	v_fma_f32 v36, v34, v40, -v36
	v_fma_f32 v37, v35, v40, v37
	v_mov_b32_e32 v40, v36
	v_mov_b32_e32 v41, v37
	v_add_f32_e32 v42, v40, v46
	v_add_f32_e32 v43, v41, v47
	ds_write_b64 v38, v[42:43] offset:512
	v_mul_f32_e32 v36, v35, v41
	v_mul_f32_e32 v37, v34, v41
	v_fma_f32 v36, v34, v40, -v36
	v_fma_f32 v37, v35, v40, v37
	v_mov_b32_e32 v40, v36
	v_mov_b32_e32 v41, v37
	v_add_f32_e32 v42, v40, v48
	v_add_f32_e32 v43, v41, v49
	ds_write_b64 v38, v[42:43] offset:0
	v_and_b32_e32 v179, 31, v181
	v_lshl_add_u32 v255, v179, 3, s26
	s_nop 1
	v_permlane32_swap_b32_e32 v152, v154
	v_permlane32_swap_b32_e32 v153, v155
	v_permlane32_swap_b32_e32 v146, v148
	v_permlane32_swap_b32_e32 v147, v149
	v_xor_b32_e32 v150, 0x80000000, v147
	v_xor_b32_e32 v151, 0x80000000, v149
	v_lshrrev_b32_e32 v179, 4, v181
	v_lshlrev_b32_e32 v179, 2, v179
	v_and_b32_e32 v225, 15, v181
	v_lshlrev_b32_e32 v225, 1, v225
	s_lshl_b32 s26, s59, 5
	v_add_u32_e32 v225, s26, v225
	s_add_i32 s27, s22, 64
	v_add_u32_e32 v204, s27, v179
	s_add_i32 s27, s22, 63
	v_sub_u32_e32 v205, s27, v179
	v_mul_u32_u24_e32 v206, 0xa00, v204
	v_mul_u32_u24_e32 v207, 0xa00, v205
	v_add_u32_e32 v179, 0x600, v225
	v_add_u32_e32 v206, v206, v179
	v_add_u32_e32 v207, v207, v179
	v_lshl_add_u32 v204, v204, 10, v225
	v_lshl_add_u32 v205, v205, 10, v225
	v_and_b32_e32 v225, 63, v209
	v_xor_b32_e32 v225, 48, v225
	v_lshlrev_b32_e32 v225, 4, v225
	s_mov_b64 s[84:85], s[78:79]
	s_mov_b32 s64, 0
	s_mov_b32 s65, -1
	s_mov_b32 s45, 0
; __device__ __forceinline__ unsigned pk2(float lo, float hi) { const f32x2 v = {lo, hi}; return __builtin_bit_cast(unsigned, __builtin_convertvector(v, bf16x2_t)); }
; __device__ __forceinline__ float bflo(unsigned w) { return __uint_as_float(w << 16); }
; __device__ __forceinline__ float bfhi(unsigned w) { return __uint_as_float(w & 0xffff0000u); }
; #define LDS_FENCE() asm volatile("s_waitcnt lgkmcnt(0)" ::: "memory")
; template <bool BWD, int MODE  >
; __device__ __forceinline__ void ssm_pass(const bf16* proj, int rowbase, int g, const bf16x8* BBp, const bf16x8* CCp, float ar, float ai, float& sr, float& si,
;                                          LAS unsigned* XS, int lane, f32x4* ysc, const float* Dp, bf16* zbuf) {
;     ...
;     for (int c = 0; c < 16; ++c) {
;         const int ch = BWD ? 15 - c : c;
;         bf16x8 unext = ucur;
;         if (c < 15) unext = *(const bf16x8*)(up + (size_t)(BWD ? ch - 1 : ch + 1) * 32 * DIN);
;         f32x4 y0 = (f32x4){0.f, 0.f, 0.f, 0.f}, y1 = y0; bf16 uvl[8];
;         if (MODE == 2) {
;             y0 = ysc[(ch * 2 + 0) * 64 + lane]; y1 = ysc[(ch * 2 + 1) * 64 + lane];
; #pragma unroll
;             for (int q = 0; q < 8; ++q) uvl[q] = proj[(size_t)(rowbase + 32 * ch + 16 * (q >> 2) + 4 * (lane >> 4) + (q & 3)) * DIN + 768 + g * 16 + (lane & 15)];
;         }
;         f32x16 z16;
; #pragma unroll
;         for (int r = 0; r < 16; ++r) z16[r] = 0.f;
;         const f32x16 x0 = __builtin_amdgcn_mfma_f32_32x32x16_bf16(ucur, bb[0], z16, 0, 0, 0);
;         const f32x16 x1 = __builtin_amdgcn_mfma_f32_32x32x16_bf16(ucur, bb[1], z16, 0, 0, 0);
;         const f32x16 x2 = __builtin_amdgcn_mfma_f32_32x32x16_bf16(ucur, bb[2], z16, 0, 0, 0);
;         const f32x16 x3 = __builtin_amdgcn_mfma_f32_32x32x16_bf16(ucur, bb[3], z16, 0, 0, 0);
; #pragma unroll
;         for (int r = 0; r < 16; ++r) { const int t = crow(r, hi); XS[t * XS_STRIDE + ql] = pk2(x0[r], x2[r]); XS[t * XS_STRIDE + 32 + ql] = pk2(x1[r], x3[r]); }
;         LDS_FENCE();
; #pragma unroll
;         for (int tt = 0; tt < 32; ++tt) {
;             const int t = BWD ? 31 - tt : tt;
;             const unsigned v = XS[t * XS_STRIDE + lane];
;             const float nr = fmaf(ar, sr, fmaf(-ai, si, bflo(v))), ni = fmaf(ar, si, fmaf(ai, sr, bfhi(v)));
;             sr = nr; si = ni;
;             if (MODE > 0) XS[t * XS_STRIDE + lane] = pk2(sr, si);
;         }
.Lp3n_block:
	s_mov_b64 exec, s[64:65]
	ds_read_b64 v[152:153], v255
	ds_read_b64 v[154:155], v255 offset:256
	v_add_u32_e32 v255, 0x200, v255
	s_mov_b64 exec, -1
	s_mov_b64 s[78:79], s[84:85]
	s_mov_b32 s32, 0
	s_waitcnt lgkmcnt(0)
.Lp3n_loopa:
	v_add_u32_e32 v156, v157, v156
	s_mov_b64 exec, s[60:61]
	global_load_dwordx4 v[138:141], v156, s[6:7]
	s_mov_b64 exec, s[62:63]
	global_load_dwordx4 v[142:145], v156, s[6:7]
	s_mov_b64 exec, -1
	v_mfma_f32_32x32x16_bf16 v[2:17], v[130:133], v[66:69], 0
	v_mfma_f32_32x32x16_bf16 v[18:33], v[130:133], v[70:73], 0
	v_mfma_f32_32x32x16_bf16 v[34:49], v[130:133], v[74:77], 0
	v_mfma_f32_32x32x16_bf16 v[50:65], v[130:133], v[78:81], 0
	v_mfma_f32_32x32x16_bf16 v[2:17], v[134:137], v[82:85], v[2:17]
	v_mfma_f32_32x32x16_bf16 v[18:33], v[134:137], v[86:89], v[18:33]
	v_mfma_f32_32x32x16_bf16 v[34:49], v[134:137], v[90:93], v[34:49]
	v_mfma_f32_32x32x16_bf16 v[50:65], v[134:137], v[94:97], v[50:65]
	s_nop 15
	s_nop 7
	v_fmac_f32_e32 v2, v150, v153
	v_fmac_f32_e32 v18, v151, v155
	v_fmac_f32_e32 v34, v147, v152
	v_fmac_f32_e32 v50, v149, v154
	v_fmac_f32_e32 v2, v146, v152
	v_fmac_f32_e32 v18, v148, v154
	v_fmac_f32_e32 v34, v146, v153
	v_fmac_f32_e32 v50, v148, v155
	v_fmac_f32_e32 v3, v150, v34
	v_fmac_f32_e32 v19, v151, v50
	v_fmac_f32_e32 v35, v147, v2
	v_fmac_f32_e32 v51, v149, v18
	v_fmac_f32_e32 v3, v146, v2
	v_fmac_f32_e32 v19, v148, v18
	v_fmac_f32_e32 v35, v146, v34
	v_fmac_f32_e32 v51, v148, v50
	v_cvt_pk_bf16_f32 v214, v2, v34
	v_cvt_pk_bf16_f32 v215, v18, v50
	ds_write2_b32 v158, v214, v215 offset0:0 offset1:32
	v_fmac_f32_e32 v4, v150, v35
	v_fmac_f32_e32 v20, v151, v51
	v_fmac_f32_e32 v36, v147, v3
	v_fmac_f32_e32 v52, v149, v19
	v_fmac_f32_e32 v4, v146, v3
	v_fmac_f32_e32 v20, v148, v19
	v_fmac_f32_e32 v36, v146, v35
	v_fmac_f32_e32 v52, v148, v51
	v_cvt_pk_bf16_f32 v216, v3, v35
	v_cvt_pk_bf16_f32 v217, v19, v51
	ds_write2_b32 v158, v216, v217 offset0:68 offset1:100
	v_fmac_f32_e32 v5, v150, v36
	v_fmac_f32_e32 v21, v151, v52
	v_fmac_f32_e32 v37, v147, v4
	v_fmac_f32_e32 v53, v149, v20
	v_fmac_f32_e32 v5, v146, v4
	v_fmac_f32_e32 v21, v148, v20
	v_fmac_f32_e32 v37, v146, v36
	v_fmac_f32_e32 v53, v148, v52
	v_cvt_pk_bf16_f32 v214, v4, v36
	v_cvt_pk_bf16_f32 v215, v20, v52
	ds_write2_b32 v158, v214, v215 offset0:136 offset1:168
	v_fmac_f32_e32 v6, v150, v37
	v_fmac_f32_e32 v22, v151, v53
	v_fmac_f32_e32 v38, v147, v5
	v_fmac_f32_e32 v54, v149, v21
	v_fmac_f32_e32 v6, v146, v5
	v_fmac_f32_e32 v22, v148, v21
	v_fmac_f32_e32 v38, v146, v37
	v_fmac_f32_e32 v54, v148, v53
	v_cvt_pk_bf16_f32 v216, v5, v37
	v_cvt_pk_bf16_f32 v217, v21, v53
	ds_write2_b32 v158, v216, v217 offset0:204 offset1:236
	v_fmac_f32_e32 v7, v150, v38
	v_fmac_f32_e32 v23, v151, v54
	v_fmac_f32_e32 v39, v147, v6
	v_fmac_f32_e32 v55, v149, v22
	v_fmac_f32_e32 v7, v146, v6
	v_fmac_f32_e32 v23, v148, v22
	v_fmac_f32_e32 v39, v146, v38
	v_fmac_f32_e32 v55, v148, v54
	v_cvt_pk_bf16_f32 v214, v6, v38
	v_cvt_pk_bf16_f32 v215, v22, v54
	ds_write2_b32 v159, v214, v215 offset0:0 offset1:32
	v_fmac_f32_e32 v8, v150, v39
	v_fmac_f32_e32 v24, v151, v55
	v_fmac_f32_e32 v40, v147, v7
	v_fmac_f32_e32 v56, v149, v23
	v_fmac_f32_e32 v8, v146, v7
	v_fmac_f32_e32 v24, v148, v23
	v_fmac_f32_e32 v40, v146, v39
	v_fmac_f32_e32 v56, v148, v55
	v_cvt_pk_bf16_f32 v216, v7, v39
	v_cvt_pk_bf16_f32 v217, v23, v55
	ds_write2_b32 v159, v216, v217 offset0:68 offset1:100
	v_fmac_f32_e32 v9, v150, v40
	v_fmac_f32_e32 v25, v151, v56
	v_fmac_f32_e32 v41, v147, v8
	v_fmac_f32_e32 v57, v149, v24
	v_fmac_f32_e32 v9, v146, v8
	v_fmac_f32_e32 v25, v148, v24
	v_fmac_f32_e32 v41, v146, v40
	v_fmac_f32_e32 v57, v148, v56
	v_cvt_pk_bf16_f32 v214, v8, v40
	v_cvt_pk_bf16_f32 v215, v24, v56
	ds_write2_b32 v159, v214, v215 offset0:136 offset1:168
	v_fmac_f32_e32 v10, v150, v41
	v_fmac_f32_e32 v26, v151, v57
	v_fmac_f32_e32 v42, v147, v9
	v_fmac_f32_e32 v58, v149, v25
	v_fmac_f32_e32 v10, v146, v9
	v_fmac_f32_e32 v26, v148, v25
	v_fmac_f32_e32 v42, v146, v41
	v_fmac_f32_e32 v58, v148, v57
	v_cvt_pk_bf16_f32 v216, v9, v41
	v_cvt_pk_bf16_f32 v217, v25, v57
	ds_write2_b32 v159, v216, v217 offset0:204 offset1:236
	v_fmac_f32_e32 v11, v150, v42
	v_fmac_f32_e32 v27, v151, v58
	v_fmac_f32_e32 v43, v147, v10
	v_fmac_f32_e32 v59, v149, v26
	v_fmac_f32_e32 v11, v146, v10
	v_fmac_f32_e32 v27, v148, v26
	v_fmac_f32_e32 v43, v146, v42
	v_fmac_f32_e32 v59, v148, v58
	v_cvt_pk_bf16_f32 v214, v10, v42
	v_cvt_pk_bf16_f32 v215, v26, v58
	ds_write2_b32 v160, v214, v215 offset0:0 offset1:32
	v_fmac_f32_e32 v12, v150, v43
	v_fmac_f32_e32 v28, v151, v59
	v_fmac_f32_e32 v44, v147, v11
	v_fmac_f32_e32 v60, v149, v27
	v_fmac_f32_e32 v12, v146, v11
	v_fmac_f32_e32 v28, v148, v27
	v_fmac_f32_e32 v44, v146, v43
	v_fmac_f32_e32 v60, v148, v59
	v_cvt_pk_bf16_f32 v216, v11, v43
	v_cvt_pk_bf16_f32 v217, v27, v59
	ds_write2_b32 v160, v216, v217 offset0:68 offset1:100
	v_fmac_f32_e32 v13, v150, v44
	v_fmac_f32_e32 v29, v151, v60
	v_fmac_f32_e32 v45, v147, v12
	v_fmac_f32_e32 v61, v149, v28
	v_fmac_f32_e32 v13, v146, v12
	v_fmac_f32_e32 v29, v148, v28
	v_fmac_f32_e32 v45, v146, v44
	v_fmac_f32_e32 v61, v148, v60
	v_cvt_pk_bf16_f32 v214, v12, v44
	v_cvt_pk_bf16_f32 v215, v28, v60
	ds_write2_b32 v160, v214, v215 offset0:136 offset1:168
	v_fmac_f32_e32 v14, v150, v45
	v_fmac_f32_e32 v30, v151, v61
	v_fmac_f32_e32 v46, v147, v13
	v_fmac_f32_e32 v62, v149, v29
	v_fmac_f32_e32 v14, v146, v13
	v_fmac_f32_e32 v30, v148, v29
	v_fmac_f32_e32 v46, v146, v45
	v_fmac_f32_e32 v62, v148, v61
	v_cvt_pk_bf16_f32 v216, v13, v45
	v_cvt_pk_bf16_f32 v217, v29, v61
	ds_write2_b32 v160, v216, v217 offset0:204 offset1:236
	v_fmac_f32_e32 v15, v150, v46
	v_fmac_f32_e32 v31, v151, v62
	v_fmac_f32_e32 v47, v147, v14
	v_fmac_f32_e32 v63, v149, v30
	v_fmac_f32_e32 v15, v146, v14
	v_fmac_f32_e32 v31, v148, v30
	v_fmac_f32_e32 v47, v146, v46
	v_fmac_f32_e32 v63, v148, v62
	v_cvt_pk_bf16_f32 v214, v14, v46
	v_cvt_pk_bf16_f32 v215, v30, v62
	ds_write2_b32 v161, v214, v215 offset0:0 offset1:32
	v_fmac_f32_e32 v16, v150, v47
	v_fmac_f32_e32 v32, v151, v63
	v_fmac_f32_e32 v48, v147, v15
	v_fmac_f32_e32 v64, v149, v31
	v_fmac_f32_e32 v16, v146, v15
	v_fmac_f32_e32 v32, v148, v31
	v_fmac_f32_e32 v48, v146, v47
	v_fmac_f32_e32 v64, v148, v63
	v_cvt_pk_bf16_f32 v216, v15, v47
	v_cvt_pk_bf16_f32 v217, v31, v63
	ds_write2_b32 v161, v216, v217 offset0:68 offset1:100
	v_fmac_f32_e32 v17, v150, v48
	v_fmac_f32_e32 v33, v151, v64
	v_fmac_f32_e32 v49, v147, v16
	v_fmac_f32_e32 v65, v149, v32
	v_fmac_f32_e32 v17, v146, v16
	v_fmac_f32_e32 v33, v148, v32
	v_fmac_f32_e32 v49, v146, v48
	v_fmac_f32_e32 v65, v148, v64
	v_cvt_pk_bf16_f32 v214, v16, v48
	v_cvt_pk_bf16_f32 v215, v32, v64
	ds_write2_b32 v161, v214, v215 offset0:136 offset1:168
	v_cvt_pk_bf16_f32 v216, v17, v49
	v_cvt_pk_bf16_f32 v217, v33, v65
	ds_write2_b32 v161, v216, v217 offset0:204 offset1:236
	v_mov_b32_e32 v152, v17
	v_mov_b32_e32 v153, v49
	v_mov_b32_e32 v154, v33
	v_mov_b32_e32 v155, v65
	s_waitcnt lgkmcnt(0)
; template <bool BWD, int MODE  >
; __device__ __forceinline__ void ssm_pass(const bf16* proj, int rowbase, int g, const bf16x8* BBp, const bf16x8* CCp, float ar, float ai, float& sr, float& si,
;                                          LAS unsigned* XS, int lane, f32x4* ysc, const float* Dp, bf16* zbuf) {
;     ...
;     for (int c = 0; c < 16; ++c) {
;         const int ch = BWD ? 15 - c : c;
;         bf16x8 unext = ucur;
;         if (c < 15) unext = *(const bf16x8*)(up + (size_t)(BWD ? ch - 1 : ch + 1) * 32 * DIN);
;         f32x4 y0 = (f32x4){0.f, 0.f, 0.f, 0.f}, y1 = y0; bf16 uvl[8];
;         if (MODE == 2) {
;             y0 = ysc[(ch * 2 + 0) * 64 + lane]; y1 = ysc[(ch * 2 + 1) * 64 + lane];
; #pragma unroll
;             for (int q = 0; q < 8; ++q) uvl[q] = proj[(size_t)(rowbase + 32 * ch + 16 * (q >> 2) + 4 * (lane >> 4) + (q & 3)) * DIN + 768 + g * 16 + (lane & 15)];
;         }
;         f32x16 z16;
; #pragma unroll
;         for (int r = 0; r < 16; ++r) z16[r] = 0.f;
;         const f32x16 x0 = __builtin_amdgcn_mfma_f32_32x32x16_bf16(ucur, bb[0], z16, 0, 0, 0);
;         const f32x16 x1 = __builtin_amdgcn_mfma_f32_32x32x16_bf16(ucur, bb[1], z16, 0, 0, 0);
;         const f32x16 x2 = __builtin_amdgcn_mfma_f32_32x32x16_bf16(ucur, bb[2], z16, 0, 0, 0);
;         const f32x16 x3 = __builtin_amdgcn_mfma_f32_32x32x16_bf16(ucur, bb[3], z16, 0, 0, 0);
; #pragma unroll
;         for (int r = 0; r < 16; ++r) { const int t = crow(r, hi); XS[t * XS_STRIDE + ql] = pk2(x0[r], x2[r]); XS[t * XS_STRIDE + 32 + ql] = pk2(x1[r], x3[r]); }
;         LDS_FENCE();
; #pragma unroll
;         for (int tt = 0; tt < 32; ++tt) {
;             const int t = BWD ? 31 - tt : tt;
;     ...
;         if (MODE > 0) {
;             LDS_FENCE();
;             const LAS unsigned char* ab = (const LAS unsigned char*)XS + (lane & 15) * (XS_STRIDE * 4) + (lane >> 4) * 16;
; #pragma unroll
;             for (int kk = 0; kk < 4; ++kk) {
;                 const bf16x8 a0 = *(const LAS bf16x8*)(ab + kk * 64), a1 = *(const LAS bf16x8*)(ab + 16 * XS_STRIDE * 4 + kk * 64);
;                 y0 = __builtin_amdgcn_mfma_f32_16x16x32_bf16(a0, cc[kk], y0, 0, 0, 0);
;                 y1 = __builtin_amdgcn_mfma_f32_16x16x32_bf16(a1, cc[kk], y1, 0, 0, 0);
;             }
;             if (MODE == 1) { ysc[(ch * 2 + 0) * 64 + lane] = y0; ysc[(ch * 2 + 1) * 64 + lane] = y1; }
	ds_read_b128 v[226:229], v178 offset:0
	ds_read_b128 v[242:245], v178 offset:4352
	ds_read_b128 v[230:233], v178 offset:64
	ds_read_b128 v[246:249], v178 offset:4416
	ds_read_b128 v[234:237], v178 offset:128
	ds_read_b128 v[250:253], v178 offset:4480
	ds_read_b128 v[238:241], v178 offset:192
	ds_read_b128 v[210:213], v178 offset:4544
	s_waitcnt lgkmcnt(6)
	v_mfma_f32_16x16x32_bf16 v[180:183], v[226:229], v[98:101], 0
	v_mfma_f32_16x16x32_bf16 v[184:187], v[242:245], v[114:117], 0
	s_waitcnt lgkmcnt(4)
	v_mfma_f32_16x16x32_bf16 v[180:183], v[230:233], v[102:105], v[180:183]
	v_mfma_f32_16x16x32_bf16 v[184:187], v[246:249], v[118:121], v[184:187]
	s_waitcnt lgkmcnt(2)
	v_mfma_f32_16x16x32_bf16 v[180:183], v[234:237], v[106:109], v[180:183]
	v_mfma_f32_16x16x32_bf16 v[184:187], v[250:253], v[122:125], v[184:187]
	s_waitcnt lgkmcnt(0)
	v_mfma_f32_16x16x32_bf16 v[180:183], v[238:241], v[110:113], v[180:183]
	v_mfma_f32_16x16x32_bf16 v[184:187], v[210:213], v[126:129], v[184:187]
	s_waitcnt vmcnt(0)
	v_mov_b32_e32 v130, v138
	v_mov_b32_e32 v131, v139
	v_mov_b32_e32 v132, v140
	v_mov_b32_e32 v133, v141
	v_mov_b32_e32 v134, v142
	v_mov_b32_e32 v135, v143
	v_mov_b32_e32 v136, v144
	v_mov_b32_e32 v137, v145
	s_nop 7
	global_store_dwordx4 v0, v[180:183], s[78:79]
	global_store_dwordx4 v0, v[184:187], s[78:79] offset:1024
	s_add_u32 s78, s78, 0x800
	s_addc_u32 s79, s79, 0
	s_add_i32 s32, s32, 1
	s_cmp_lt_u32 s32, 4
	s_cbranch_scc1 .Lp3n_loopa
	s_waitcnt vmcnt(0)
	s_sub_u32 s78, s78, 0x800
	s_subb_u32 s79, s79, 0
.Lp3n_loopb:
	s_cmp_lg_u32 s32, 7
	s_cbranch_scc1 .Lp3n_nofixb
	s_cmp_eq_u32 s45, 3
	s_cbranch_scc1 .Lp3n_nopfb
	s_mov_b64 exec, s[62:63]
	v_add_u32_e32 v156, 0xa0000, v156
	s_mov_b64 exec, -1
.Lp3n_nofixb:
	v_add_u32_e32 v156, v157, v156
	s_mov_b64 exec, s[60:61]
	global_load_dwordx4 v[138:141], v156, s[6:7]
	s_mov_b64 exec, s[62:63]
	global_load_dwordx4 v[142:145], v156, s[6:7]
	s_mov_b64 exec, -1
.Lp3n_nopfb:
	global_load_dwordx4 v[188:191], v225, s[78:79] offset:1024
	global_load_dwordx4 v[192:195], v225, s[78:79]
	global_load_ushort v196, v206, s[6:7]
	global_load_ushort v197, v206, s[6:7] offset:2560
	global_load_ushort v198, v206, s[80:81]
	global_load_ushort v199, v206, s[80:81] offset:2560
	global_load_ushort v200, v207, s[6:7]
	global_load_ushort v201, v207, s[6:7] offset:-2560
	global_load_ushort v202, v207, s[82:83]
	global_load_ushort v203, v207, s[82:83] offset:-2560
	v_mfma_f32_32x32x16_bf16 v[2:17], v[130:133], v[66:69], 0
	v_mfma_f32_32x32x16_bf16 v[18:33], v[130:133], v[70:73], 0
	v_mfma_f32_32x32x16_bf16 v[34:49], v[130:133], v[74:77], 0
	v_mfma_f32_32x32x16_bf16 v[50:65], v[130:133], v[78:81], 0
	v_mfma_f32_32x32x16_bf16 v[2:17], v[134:137], v[82:85], v[2:17]
	v_mfma_f32_32x32x16_bf16 v[18:33], v[134:137], v[86:89], v[18:33]
	v_mfma_f32_32x32x16_bf16 v[34:49], v[134:137], v[90:93], v[34:49]
	v_mfma_f32_32x32x16_bf16 v[50:65], v[134:137], v[94:97], v[50:65]
	s_nop 15
	s_nop 7
	v_fmac_f32_e32 v2, v150, v153
	v_fmac_f32_e32 v18, v151, v155
	v_fmac_f32_e32 v34, v147, v152
	v_fmac_f32_e32 v50, v149, v154
	v_fmac_f32_e32 v2, v146, v152
	v_fmac_f32_e32 v18, v148, v154
	v_fmac_f32_e32 v34, v146, v153
	v_fmac_f32_e32 v50, v148, v155
	v_fmac_f32_e32 v3, v150, v34
	v_fmac_f32_e32 v19, v151, v50
	v_fmac_f32_e32 v35, v147, v2
	v_fmac_f32_e32 v51, v149, v18
	v_fmac_f32_e32 v3, v146, v2
	v_fmac_f32_e32 v19, v148, v18
	v_fmac_f32_e32 v35, v146, v34
	v_fmac_f32_e32 v51, v148, v50
	v_cvt_pk_bf16_f32 v214, v2, v34
	v_cvt_pk_bf16_f32 v215, v18, v50
	ds_write2_b32 v158, v214, v215 offset0:0 offset1:32
	v_fmac_f32_e32 v4, v150, v35
	v_fmac_f32_e32 v20, v151, v51
	v_fmac_f32_e32 v36, v147, v3
	v_fmac_f32_e32 v52, v149, v19
	v_fmac_f32_e32 v4, v146, v3
	v_fmac_f32_e32 v20, v148, v19
	v_fmac_f32_e32 v36, v146, v35
	v_fmac_f32_e32 v52, v148, v51
	v_cvt_pk_bf16_f32 v216, v3, v35
	v_cvt_pk_bf16_f32 v217, v19, v51
	ds_write2_b32 v158, v216, v217 offset0:68 offset1:100
	v_fmac_f32_e32 v5, v150, v36
	v_fmac_f32_e32 v21, v151, v52
	v_fmac_f32_e32 v37, v147, v4
	v_fmac_f32_e32 v53, v149, v20
	v_fmac_f32_e32 v5, v146, v4
	v_fmac_f32_e32 v21, v148, v20
	v_fmac_f32_e32 v37, v146, v36
	v_fmac_f32_e32 v53, v148, v52
	v_cvt_pk_bf16_f32 v214, v4, v36
	v_cvt_pk_bf16_f32 v215, v20, v52
	ds_write2_b32 v158, v214, v215 offset0:136 offset1:168
	v_fmac_f32_e32 v6, v150, v37
	v_fmac_f32_e32 v22, v151, v53
	v_fmac_f32_e32 v38, v147, v5
	v_fmac_f32_e32 v54, v149, v21
	v_fmac_f32_e32 v6, v146, v5
	v_fmac_f32_e32 v22, v148, v21
	v_fmac_f32_e32 v38, v146, v37
	v_fmac_f32_e32 v54, v148, v53
	v_cvt_pk_bf16_f32 v216, v5, v37
	v_cvt_pk_bf16_f32 v217, v21, v53
	ds_write2_b32 v158, v216, v217 offset0:204 offset1:236
	v_fmac_f32_e32 v7, v150, v38
	v_fmac_f32_e32 v23, v151, v54
	v_fmac_f32_e32 v39, v147, v6
	v_fmac_f32_e32 v55, v149, v22
	v_fmac_f32_e32 v7, v146, v6
	v_fmac_f32_e32 v23, v148, v22
	v_fmac_f32_e32 v39, v146, v38
	v_fmac_f32_e32 v55, v148, v54
	v_cvt_pk_bf16_f32 v214, v6, v38
	v_cvt_pk_bf16_f32 v215, v22, v54
	ds_write2_b32 v159, v214, v215 offset0:0 offset1:32
	v_fmac_f32_e32 v8, v150, v39
	v_fmac_f32_e32 v24, v151, v55
	v_fmac_f32_e32 v40, v147, v7
	v_fmac_f32_e32 v56, v149, v23
	v_fmac_f32_e32 v8, v146, v7
	v_fmac_f32_e32 v24, v148, v23
	v_fmac_f32_e32 v40, v146, v39
	v_fmac_f32_e32 v56, v148, v55
	v_cvt_pk_bf16_f32 v216, v7, v39
	v_cvt_pk_bf16_f32 v217, v23, v55
	ds_write2_b32 v159, v216, v217 offset0:68 offset1:100
	v_fmac_f32_e32 v9, v150, v40
	v_fmac_f32_e32 v25, v151, v56
	v_fmac_f32_e32 v41, v147, v8
	v_fmac_f32_e32 v57, v149, v24
	v_fmac_f32_e32 v9, v146, v8
	v_fmac_f32_e32 v25, v148, v24
	v_fmac_f32_e32 v41, v146, v40
	v_fmac_f32_e32 v57, v148, v56
; #define LAS __attribute__((address_space(3)))
; __device__ __forceinline__ unsigned pk2(float lo, float hi) { const f32x2 v = {lo, hi}; return __builtin_bit_cast(unsigned, __builtin_convertvector(v, bf16x2_t)); }
; __device__ __forceinline__ float bflo(unsigned w) { return __uint_as_float(w << 16); }
; __device__ __forceinline__ float bfhi(unsigned w) { return __uint_as_float(w & 0xffff0000u); }
; #define LDS_FENCE() asm volatile("s_waitcnt lgkmcnt(0)" ::: "memory")
; __device__ __forceinline__ int crow(int r, int hi) { return (r & 3) + 8 * (r >> 2) + 4 * hi; }
; template <bool BWD, int MODE  >
; __device__ __forceinline__ void ssm_pass(const bf16* proj, int rowbase, int g, const bf16x8* BBp, const bf16x8* CCp, float ar, float ai, float& sr, float& si,
;                                          LAS unsigned* XS, int lane, f32x4* ysc, const float* Dp, bf16* zbuf) {
;     ...
;         for (int r = 0; r < 16; ++r) { const int t = crow(r, hi); XS[t * XS_STRIDE + ql] = pk2(x0[r], x2[r]); XS[t * XS_STRIDE + 32 + ql] = pk2(x1[r], x3[r]); }
;         LDS_FENCE();
; #pragma unroll
;         for (int tt = 0; tt < 32; ++tt) {
;             const int t = BWD ? 31 - tt : tt;
;             const unsigned v = XS[t * XS_STRIDE + lane];
;             const float nr = fmaf(ar, sr, fmaf(-ai, si, bflo(v))), ni = fmaf(ar, si, fmaf(ai, sr, bfhi(v)));
;             sr = nr; si = ni;
;             if (MODE > 0) XS[t * XS_STRIDE + lane] = pk2(sr, si);
;         }
;         if (MODE > 0) {
;             LDS_FENCE();
;             const LAS unsigned char* ab = (const LAS unsigned char*)XS + (lane & 15) * (XS_STRIDE * 4) + (lane >> 4) * 16;
; #pragma unroll
;             for (int kk = 0; kk < 4; ++kk) {
;                 const bf16x8 a0 = *(const LAS bf16x8*)(ab + kk * 64), a1 = *(const LAS bf16x8*)(ab + 16 * XS_STRIDE * 4 + kk * 64);
;                 y0 = __builtin_amdgcn_mfma_f32_16x16x32_bf16(a0, cc[kk], y0, 0, 0, 0);
;                 y1 = __builtin_amdgcn_mfma_f32_16x16x32_bf16(a1, cc[kk], y1, 0, 0, 0);
;             }
	v_cvt_pk_bf16_f32 v214, v8, v40
	v_cvt_pk_bf16_f32 v215, v24, v56
	ds_write2_b32 v159, v214, v215 offset0:136 offset1:168
	v_fmac_f32_e32 v10, v150, v41
	v_fmac_f32_e32 v26, v151, v57
	v_fmac_f32_e32 v42, v147, v9
	v_fmac_f32_e32 v58, v149, v25
	v_fmac_f32_e32 v10, v146, v9
	v_fmac_f32_e32 v26, v148, v25
	v_fmac_f32_e32 v42, v146, v41
	v_fmac_f32_e32 v58, v148, v57
	v_cvt_pk_bf16_f32 v216, v9, v41
	v_cvt_pk_bf16_f32 v217, v25, v57
	ds_write2_b32 v159, v216, v217 offset0:204 offset1:236
	v_fmac_f32_e32 v11, v150, v42
	v_fmac_f32_e32 v27, v151, v58
	v_fmac_f32_e32 v43, v147, v10
	v_fmac_f32_e32 v59, v149, v26
	v_fmac_f32_e32 v11, v146, v10
	v_fmac_f32_e32 v27, v148, v26
	v_fmac_f32_e32 v43, v146, v42
	v_fmac_f32_e32 v59, v148, v58
	v_cvt_pk_bf16_f32 v214, v10, v42
	v_cvt_pk_bf16_f32 v215, v26, v58
	ds_write2_b32 v160, v214, v215 offset0:0 offset1:32
	v_fmac_f32_e32 v12, v150, v43
	v_fmac_f32_e32 v28, v151, v59
	v_fmac_f32_e32 v44, v147, v11
	v_fmac_f32_e32 v60, v149, v27
	v_fmac_f32_e32 v12, v146, v11
	v_fmac_f32_e32 v28, v148, v27
	v_fmac_f32_e32 v44, v146, v43
	v_fmac_f32_e32 v60, v148, v59
	v_cvt_pk_bf16_f32 v216, v11, v43
	v_cvt_pk_bf16_f32 v217, v27, v59
	ds_write2_b32 v160, v216, v217 offset0:68 offset1:100
	v_fmac_f32_e32 v13, v150, v44
	v_fmac_f32_e32 v29, v151, v60
	v_fmac_f32_e32 v45, v147, v12
	v_fmac_f32_e32 v61, v149, v28
	v_fmac_f32_e32 v13, v146, v12
	v_fmac_f32_e32 v29, v148, v28
	v_fmac_f32_e32 v45, v146, v44
	v_fmac_f32_e32 v61, v148, v60
	v_cvt_pk_bf16_f32 v214, v12, v44
	v_cvt_pk_bf16_f32 v215, v28, v60
	ds_write2_b32 v160, v214, v215 offset0:136 offset1:168
	v_fmac_f32_e32 v14, v150, v45
	v_fmac_f32_e32 v30, v151, v61
	v_fmac_f32_e32 v46, v147, v13
	v_fmac_f32_e32 v62, v149, v29
	v_fmac_f32_e32 v14, v146, v13
	v_fmac_f32_e32 v30, v148, v29
	v_fmac_f32_e32 v46, v146, v45
	v_fmac_f32_e32 v62, v148, v61
	v_cvt_pk_bf16_f32 v216, v13, v45
	v_cvt_pk_bf16_f32 v217, v29, v61
	ds_write2_b32 v160, v216, v217 offset0:204 offset1:236
	v_fmac_f32_e32 v15, v150, v46
	v_fmac_f32_e32 v31, v151, v62
	v_fmac_f32_e32 v47, v147, v14
	v_fmac_f32_e32 v63, v149, v30
	v_fmac_f32_e32 v15, v146, v14
	v_fmac_f32_e32 v31, v148, v30
	v_fmac_f32_e32 v47, v146, v46
	v_fmac_f32_e32 v63, v148, v62
	v_cvt_pk_bf16_f32 v214, v14, v46
	v_cvt_pk_bf16_f32 v215, v30, v62
	ds_write2_b32 v161, v214, v215 offset0:0 offset1:32
	v_fmac_f32_e32 v16, v150, v47
	v_fmac_f32_e32 v32, v151, v63
	v_fmac_f32_e32 v48, v147, v15
	v_fmac_f32_e32 v64, v149, v31
	v_fmac_f32_e32 v16, v146, v15
	v_fmac_f32_e32 v32, v148, v31
	v_fmac_f32_e32 v48, v146, v47
	v_fmac_f32_e32 v64, v148, v63
	v_cvt_pk_bf16_f32 v216, v15, v47
	v_cvt_pk_bf16_f32 v217, v31, v63
	ds_write2_b32 v161, v216, v217 offset0:68 offset1:100
	v_fmac_f32_e32 v17, v150, v48
	v_fmac_f32_e32 v33, v151, v64
	v_fmac_f32_e32 v49, v147, v16
	v_fmac_f32_e32 v65, v149, v32
	v_fmac_f32_e32 v17, v146, v16
	v_fmac_f32_e32 v33, v148, v32
	v_fmac_f32_e32 v49, v146, v48
	v_fmac_f32_e32 v65, v148, v64
	v_cvt_pk_bf16_f32 v214, v16, v48
	v_cvt_pk_bf16_f32 v215, v32, v64
	ds_write2_b32 v161, v214, v215 offset0:136 offset1:168
	v_cvt_pk_bf16_f32 v216, v17, v49
	v_cvt_pk_bf16_f32 v217, v33, v65
	ds_write2_b32 v161, v216, v217 offset0:204 offset1:236
	v_mov_b32_e32 v152, v17
	v_mov_b32_e32 v153, v49
	v_mov_b32_e32 v154, v33
	v_mov_b32_e32 v155, v65
	s_waitcnt lgkmcnt(0)
	ds_read_b128 v[226:229], v178 offset:0
	ds_read_b128 v[242:245], v178 offset:4352
	ds_read_b128 v[230:233], v178 offset:64
	ds_read_b128 v[246:249], v178 offset:4416
	ds_read_b128 v[234:237], v178 offset:128
	ds_read_b128 v[250:253], v178 offset:4480
	ds_read_b128 v[238:241], v178 offset:192
	ds_read_b128 v[210:213], v178 offset:4544
	s_waitcnt lgkmcnt(6)
	v_mfma_f32_16x16x32_bf16 v[180:183], v[226:229], v[98:101], 0
	v_mfma_f32_16x16x32_bf16 v[184:187], v[242:245], v[114:117], 0
	s_waitcnt lgkmcnt(4)
	v_mfma_f32_16x16x32_bf16 v[180:183], v[230:233], v[102:105], v[180:183]
	v_mfma_f32_16x16x32_bf16 v[184:187], v[246:249], v[118:121], v[184:187]
	s_waitcnt lgkmcnt(2)
	v_mfma_f32_16x16x32_bf16 v[180:183], v[234:237], v[106:109], v[180:183]
	v_mfma_f32_16x16x32_bf16 v[184:187], v[250:253], v[122:125], v[184:187]
	s_waitcnt lgkmcnt(0)
	v_mfma_f32_16x16x32_bf16 v[180:183], v[238:241], v[110:113], v[180:183]
	v_mfma_f32_16x16x32_bf16 v[184:187], v[210:213], v[126:129], v[184:187]
	s_waitcnt vmcnt(0)
; __device__ __forceinline__ unsigned f2bf(float f) { unsigned u = __builtin_bit_cast(unsigned, f); return (u + 0x7fffu + ((u >> 16) & 1u)) >> 16; }
; __device__ __forceinline__ float bf2f(bf16 v) { return __uint_as_float((unsigned)v << 16); }
; template <bool BWD, int MODE  >
; __device__ __forceinline__ void ssm_pass(const bf16* proj, int rowbase, int g, const bf16x8* BBp, const bf16x8* CCp, float ar, float ai, float& sr, float& si,
;                                          LAS unsigned* XS, int lane, f32x4* ysc, const float* Dp, bf16* zbuf) {
;     ...
;             if (MODE == 1) { ysc[(ch * 2 + 0) * 64 + lane] = y0; ysc[(ch * 2 + 1) * 64 + lane] = y1; }
;             else {
;                 const int hcol = g * 16 + (lane & 15);
; #pragma unroll
;                 for (int rt = 0; rt < 2; ++rt)
; #pragma unroll
;                     for (int i = 0; i < 4; ++i) {
;                         const int row = rowbase + 32 * ch + 16 * rt + 4 * (lane >> 4) + i;
;                         const float uv = bf2f(uvl[rt * 4 + i]);
;                         const float y = (rt ? y1[i] : y0[i]) + dval * uv;
;                         const float zz = y * __builtin_amdgcn_rcpf(1.0f + __builtin_amdgcn_exp2f(-2.3022082f * (y + 0.044715f * y * y * y)));
;                         zbuf[(size_t)row * 512 + hcol] = (bf16)f2bf(zz);
;                     }
	v_mov_b32_e32 v130, v138
	v_mov_b32_e32 v131, v139
	v_mov_b32_e32 v132, v140
	v_mov_b32_e32 v133, v141
	v_mov_b32_e32 v134, v142
	v_mov_b32_e32 v135, v143
	v_mov_b32_e32 v136, v144
	v_mov_b32_e32 v137, v145
	s_nop 7
	v_add_f32_e32 v180, v180, v191
	v_add_f32_e32 v181, v181, v190
	v_add_f32_e32 v182, v182, v189
	v_add_f32_e32 v183, v183, v188
	v_add_f32_e32 v184, v184, v195
	v_add_f32_e32 v185, v185, v194
	v_add_f32_e32 v186, v186, v193
	v_add_f32_e32 v187, v187, v192
	v_lshlrev_b32_e32 v196, 16, v196
	v_lshlrev_b32_e32 v197, 16, v197
	v_lshlrev_b32_e32 v198, 16, v198
	v_lshlrev_b32_e32 v199, 16, v199
	v_lshlrev_b32_e32 v200, 16, v200
	v_lshlrev_b32_e32 v201, 16, v201
	v_lshlrev_b32_e32 v202, 16, v202
	v_lshlrev_b32_e32 v203, 16, v203
	v_fmac_f32_e32 v180, v208, v196
	v_fmac_f32_e32 v181, v208, v197
	v_fmac_f32_e32 v182, v208, v198
	v_fmac_f32_e32 v183, v208, v199
	v_fmac_f32_e32 v184, v208, v200
	v_fmac_f32_e32 v185, v208, v201
	v_fmac_f32_e32 v186, v208, v202
	v_fmac_f32_e32 v187, v208, v203
	v_mul_f32_e32 v226, 0x3d372713, v180
	v_mul_f32_e32 v227, 0x3d372713, v181
	v_mul_f32_e32 v228, 0x3d372713, v182
	v_mul_f32_e32 v229, 0x3d372713, v183
	v_mul_f32_e32 v230, 0x3d372713, v184
	v_mul_f32_e32 v231, 0x3d372713, v185
	v_mul_f32_e32 v232, 0x3d372713, v186
	v_mul_f32_e32 v233, 0x3d372713, v187
	v_mul_f32_e32 v226, v180, v226
	v_mul_f32_e32 v227, v181, v227
	v_mul_f32_e32 v228, v182, v228
	v_mul_f32_e32 v229, v183, v229
	v_mul_f32_e32 v230, v184, v230
	v_mul_f32_e32 v231, v185, v231
	v_mul_f32_e32 v232, v186, v232
	v_mul_f32_e32 v233, v187, v233
	v_fma_f32 v226, v180, v226, v180
	v_fma_f32 v227, v181, v227, v181
	v_fma_f32 v228, v182, v228, v182
	v_fma_f32 v229, v183, v229, v183
	v_fma_f32 v230, v184, v230, v184
	v_fma_f32 v231, v185, v231, v185
	v_fma_f32 v232, v186, v232, v186
	v_fma_f32 v233, v187, v233, v187
	v_mul_f32_e32 v226, 0xc0135761, v226
	v_mul_f32_e32 v227, 0xc0135761, v227
	v_mul_f32_e32 v228, 0xc0135761, v228
	v_mul_f32_e32 v229, 0xc0135761, v229
	v_mul_f32_e32 v230, 0xc0135761, v230
	v_mul_f32_e32 v231, 0xc0135761, v231
	v_mul_f32_e32 v232, 0xc0135761, v232
	v_mul_f32_e32 v233, 0xc0135761, v233
	v_exp_f32_e32 v226, v226
	v_exp_f32_e32 v227, v227
	v_exp_f32_e32 v228, v228
	v_exp_f32_e32 v229, v229
	v_exp_f32_e32 v230, v230
	v_exp_f32_e32 v231, v231
	v_exp_f32_e32 v232, v232
	v_exp_f32_e32 v233, v233
	v_add_f32_e32 v226, 1.0, v226
	v_add_f32_e32 v227, 1.0, v227
	v_add_f32_e32 v228, 1.0, v228
	v_add_f32_e32 v229, 1.0, v229
	v_add_f32_e32 v230, 1.0, v230
	v_add_f32_e32 v231, 1.0, v231
	v_add_f32_e32 v232, 1.0, v232
	v_add_f32_e32 v233, 1.0, v233
	v_rcp_f32_e32 v226, v226
	v_rcp_f32_e32 v227, v227
	v_rcp_f32_e32 v228, v228
	v_rcp_f32_e32 v229, v229
	v_rcp_f32_e32 v230, v230
	v_rcp_f32_e32 v231, v231
	v_rcp_f32_e32 v232, v232
	v_rcp_f32_e32 v233, v233
	v_mul_f32_e32 v226, v180, v226
	v_mul_f32_e32 v227, v181, v227
	v_mul_f32_e32 v228, v182, v228
	v_mul_f32_e32 v229, v183, v229
	v_mul_f32_e32 v230, v184, v230
	v_mul_f32_e32 v231, v185, v231
	v_mul_f32_e32 v232, v186, v232
	v_mul_f32_e32 v233, v187, v233
	v_cvt_pk_bf16_f32 v226, v226, v226
	v_cvt_pk_bf16_f32 v227, v227, v227
	v_cvt_pk_bf16_f32 v228, v228, v228
	v_cvt_pk_bf16_f32 v229, v229, v229
	v_cvt_pk_bf16_f32 v230, v230, v230
	v_cvt_pk_bf16_f32 v231, v231, v231
	v_cvt_pk_bf16_f32 v232, v232, v232
	v_cvt_pk_bf16_f32 v233, v233, v233
	global_store_short v204, v226, s[8:9]
	global_store_short v204, v227, s[8:9] offset:1024
	global_store_short v204, v228, s[8:9] offset:2048
	global_store_short v204, v229, s[8:9] offset:3072
	global_store_short v205, v230, s[8:9]
	global_store_short v205, v231, s[8:9] offset:-1024
	global_store_short v205, v232, s[8:9] offset:-2048
	global_store_short v205, v233, s[8:9] offset:-3072
	v_add_u32_e32 v204, 0x4000, v204
	v_add_u32_e32 v205, 0xffffc000, v205
	v_add_u32_e32 v206, 0xa000, v206
	v_add_u32_e32 v207, 0xffff6000, v207
	s_sub_u32 s78, s78, 0x800
	s_subb_u32 s79, s79, 0
	s_add_i32 s32, s32, 1
	s_cmp_lt_u32 s32, 8
	s_cbranch_scc1 .Lp3n_loopb
	v_add_u32_e32 v204, 0x10000, v204
	v_add_u32_e32 v205, 0x30000, v205
	v_add_u32_e32 v206, 0x28000, v206
	v_add_u32_e32 v207, 0x78000, v207
	s_add_i32 s45, s45, 1
	s_cmp_lt_u32 s45, 4
	s_cbranch_scc1 .Lp3n_block
	s_add_i32 s58, s58, s20
	s_cmpk_gt_i32 s58, 0xff
	s_cbranch_scc0 .Lp3n_task

; __global__ void __launch_bounds__(NTHREADS, 2) hymba_fwd(Args a) {
	.amdhsa_kernel _Z9hymba_fwd4Args
		.amdhsa_group_segment_fixed_size 0
		.amdhsa_private_segment_fixed_size 0
		.amdhsa_kernarg_size 488
		.amdhsa_user_sgpr_count 2
		.amdhsa_user_sgpr_dispatch_ptr 0
		.amdhsa_user_sgpr_queue_ptr 0
		.amdhsa_user_sgpr_kernarg_segment_ptr 1
		.amdhsa_user_sgpr_dispatch_id 0
		.amdhsa_user_sgpr_kernarg_preload_length 0
		.amdhsa_user_sgpr_kernarg_preload_offset 0
		.amdhsa_user_sgpr_private_segment_size 0
		.amdhsa_uses_dynamic_stack 0
		.amdhsa_enable_private_segment 0
		.amdhsa_system_sgpr_workgroup_id_x 1
		.amdhsa_system_sgpr_workgroup_id_y 0
		.amdhsa_system_sgpr_workgroup_id_z 0
		.amdhsa_system_sgpr_workgroup_info 0
		.amdhsa_system_vgpr_workitem_id 2
		.amdhsa_next_free_vgpr 256
		.amdhsa_next_free_sgpr 102
		.amdhsa_accum_offset 256
		.amdhsa_reserve_vcc 1
		.amdhsa_float_round_mode_32 0
		.amdhsa_float_round_mode_16_64 0
		.amdhsa_float_denorm_mode_32 3
		.amdhsa_float_denorm_mode_16_64 3
		.amdhsa_dx10_clamp 1
		.amdhsa_ieee_mode 1
		.amdhsa_fp16_overflow 0
		.amdhsa_tg_split 0
		.amdhsa_exception_fp_ieee_invalid_op 0
		.amdhsa_exception_fp_denorm_src 0
		.amdhsa_exception_fp_ieee_div_zero 0
		.amdhsa_exception_fp_ieee_overflow 0
		.amdhsa_exception_fp_ieee_underflow 0
		.amdhsa_exception_fp_ieee_inexact 0
		.amdhsa_exception_int_div_zero 0
	.end_amdhsa_kernel

; __global__ void __launch_bounds__(NTHREADS, 2) hymba_fwd(Args a) {
amdhsa.kernels:
  - .agpr_count:     0
    .args:
      - .offset:         0
        .size:           232
        .value_kind:     by_value
      - .offset:         232
        .size:           4
        .value_kind:     hidden_block_count_x
      - .offset:         236
        .size:           4
        .value_kind:     hidden_block_count_y
      - .offset:         240
        .size:           4
        .value_kind:     hidden_block_count_z
      - .offset:         244
        .size:           2
        .value_kind:     hidden_group_size_x
      - .offset:         246
        .size:           2
        .value_kind:     hidden_group_size_y
      - .offset:         248
        .size:           2
        .value_kind:     hidden_group_size_z
      - .offset:         250
        .size:           2
        .value_kind:     hidden_remainder_x
      - .offset:         252
        .size:           2
        .value_kind:     hidden_remainder_y
      - .offset:         254
        .size:           2
        .value_kind:     hidden_remainder_z
      - .offset:         272
        .size:           8
        .value_kind:     hidden_global_offset_x
      - .offset:         280
        .size:           8
        .value_kind:     hidden_global_offset_y
      - .offset:         288
        .size:           8
        .value_kind:     hidden_global_offset_z
      - .offset:         296
        .size:           2
        .value_kind:     hidden_grid_dims
      - .offset:         320
        .size:           8
        .value_kind:     hidden_multigrid_sync_arg
      - .offset:         352
        .size:           4
        .value_kind:     hidden_dynamic_lds_size
    .group_segment_fixed_size: 0
    .kernarg_segment_align: 8
    .kernarg_segment_size: 488
    .language:       OpenCL C
    .language_version:
      - 2
      - 0
    .max_flat_workgroup_size: 512
    .name:           _Z9hymba_fwd4Args
    .private_segment_fixed_size: 0
    .sgpr_count:     108
    .sgpr_spill_count: 33
    .symbol:         _Z9hymba_fwd4Args.kd
    .uniform_work_group_size: 1
    .uses_dynamic_stack: false
    .vgpr_count:     256
    .vgpr_spill_count: 0
    .wavefront_size: 64
